# plus: LayerNorm wave sums by DPP adds and permlane swaps instead of six ds_bpermute round trips
# baseline (speedup 1.0000x reference)
; #define GAS __attribute__((address_space(1)))
; #define WSB(F, off) ((bf16*)(wsq((F).ws) + (off)))
; __device__ __forceinline__ void ln_rows(const Frame& F, int idx, bool final_out, int row_lo, int row_hi, int gw0, int NGW, bool comb = false) {
;     ...
;     for (int m0 = row_lo + gw; m0 < row_hi; m0 += 2 * NGW) {
;         v4u w[2][2]; const bool two = m0 + NGW < row_hi;
; #pragma unroll
;         for (int r = 0; r < 2; ++r) { const int m = (r == 0 || two) ? m0 + r * NGW : m0; const GAS v4u* yr = (const GAS v4u*)(WSB(F, comb ? WS_HB : WS_YB) + (size_t)m * D) + tc.lane; w[r][0] = yr[0]; w[r][1] = yr[64]; }
; #pragma unroll
;         for (int r = 0; r < 2; ++r) { const int m = m0 + r * NGW; if (r == 1 && !two) break;
;         f32x4 v[4]; float s = 0.f;
; #pragma unroll
;         for (int j = 0; j < 2; ++j) { const v4u x = w[r][j]; v[2 * j] = (f32x4){bflo(x.x), bfhi(x.x), bflo(x.y), bfhi(x.y)}; v[2 * j + 1] = (f32x4){bflo(x.z), bfhi(x.z), bflo(x.w), bfhi(x.w)}; }
;         if (comb) {
;             const GAS f32x4* pa = (const GAS f32x4*)((const float*)WSB(F, WS_ACT) + (size_t)(m - MP) * D) + 2 * tc.lane; const GAS f32x4* pb = pa + (size_t)512 * D / 4;
; #pragma unroll
;             for (int j = 0; j < 2; ++j) { v[2 * j] = v[2 * j] * ALPHA + (pa[128 * j] + pb[128 * j]) * 0.5f; v[2 * j + 1] = v[2 * j + 1] * ALPHA + (pa[128 * j + 1] + pb[128 * j + 1]) * 0.5f; } }
; #pragma unroll
;         for (int j = 0; j < 4; ++j) s += (v[j].x + v[j].y) + (v[j].z + v[j].w);
;         const float mean = wave_sum(s) * (1.f / D); float s2 = 0.f;
; #pragma unroll
;         for (int j = 0; j < 4; ++j) { v[j] = v[j] - mean; s2 += (v[j].x * v[j].x + v[j].y * v[j].y) + (v[j].z * v[j].z + v[j].w * v[j].w); }
;         const float rstd = 1.f / sqrtf(wave_sum(s2) * (1.f / D) + LN_EPS);
.LBB0_296:
	v_readlane_b32 s4, v253, 7
	s_add_i32 s4, s4, s10
	s_add_i32 s6, s4, 0xffffff80
	s_mov_b64 s[4:5], s[46:47]
	s_add_u32 s4, s4, s2
	s_addc_u32 s5, s5, s3
	v_lshlrev_b64 v[44:45], 4, v[42:43]
	v_lshl_add_u64 v[34:35], s[4:5], 0, v[44:45]
	s_mov_b32 s4, 0xf7f00000
	s_mov_b32 s5, -1
	v_lshl_add_u64 v[36:37], v[34:35], 0, s[4:5]
	s_mov_b32 s4, 0xf7f00000
	v_add_co_u32_e32 v34, vcc, s4, v34
	s_cmp_lt_i32 s6, 0x10000
	s_nop 0
	v_addc_co_u32_e32 v35, vcc, -1, v35, vcc
	global_load_dwordx4 v[60:63], v[34:35], off
	global_load_dwordx4 v[46:49], v[36:37], off offset:1024
	v_readlane_b32 s4, v253, 15
	s_cselect_b32 s4, s4, 0
	s_add_i32 s4, s4, s10
	s_ashr_i32 s5, s4, 31
	s_mov_b64 s[8:9], s[46:47]
	s_lshl_b64 s[4:5], s[4:5], 11
	s_add_u32 s4, s8, s4
	s_addc_u32 s5, s9, s5
	v_lshl_add_u64 v[34:35], s[4:5], 0, v[44:45]
	s_mov_b64 s[4:5], 0x100000
	v_lshl_add_u64 v[38:39], v[34:35], 0, s[4:5]
	s_mov_b32 s4, 0x100000
	v_add_co_u32_e32 v34, vcc, s4, v34
	s_mov_b64 s[4:5], s[46:47]
	s_nop 0
	v_addc_co_u32_e32 v35, vcc, 0, v35, vcc
	global_load_dwordx4 v[34:37], v[34:35], off
	s_nop 0
	global_load_dwordx4 v[38:41], v[38:39], off offset:1024
	s_add_u32 s8, s4, s2
	s_addc_u32 s9, s5, s3
	s_cmp_gt_i32 s6, 0xffff
	s_waitcnt vmcnt(0)
	v_lshlrev_b32_e32 v59, 16, v61
	v_lshlrev_b32_e32 v58, 16, v60
	v_and_b32_e32 v65, 0xffff0000, v61
	v_and_b32_e32 v64, 0xffff0000, v60
	v_pk_add_f32 v[60:61], v[58:59], v[64:65]
	v_lshlrev_b32_e32 v54, 16, v46
	v_add_f32_e32 v1, v60, v61
	v_lshlrev_b32_e32 v61, 16, v63
	v_lshlrev_b32_e32 v60, 16, v62
	v_and_b32_e32 v63, 0xffff0000, v63
	v_and_b32_e32 v62, 0xffff0000, v62
	v_and_b32_e32 v55, 0xffff0000, v46
	v_lshlrev_b32_e32 v56, 16, v47
	v_and_b32_e32 v57, 0xffff0000, v47
	v_pk_add_f32 v[66:67], v[60:61], v[62:63]
	v_lshlrev_b32_e32 v50, 16, v48
	v_and_b32_e32 v52, 0xffff0000, v48
	v_lshlrev_b32_e32 v46, 16, v49
	v_and_b32_e32 v48, 0xffff0000, v49
	v_add_f32_e32 v49, 0, v1
	v_pk_add_f32 v[66:67], v[66:67], v[66:67] op_sel_hi:[0,1]
	v_add_f32_e32 v51, v54, v55
	v_add_f32_e32 v53, v56, v57
	v_and_b32_e32 v1, 64, v239
	v_pk_add_f32 v[68:69], v[50:51], v[52:53]
	v_mov_b32_e32 v47, v67
	v_add_u32_e32 v51, 64, v1
	v_xor_b32_e32 v1, 1, v239
	v_pk_add_f32 v[66:67], v[46:47], v[48:49]
	v_cmp_lt_i32_e32 vcc, v1, v51
	v_pk_add_f32 v[66:67], v[68:69], v[66:67]
	s_nop 0
	v_cndmask_b32_e32 v1, v239, v1, vcc
	v_add_f32_e32 v47, v66, v67
	v_lshlrev_b32_e32 v1, 2, v1
	s_nop 1
	v_add_f32_dpp v47, v47, v47 quad_perm:[1,0,3,2] row_mask:0xf bank_mask:0xf
	s_nop 1
	v_add_f32_dpp v47, v47, v47 quad_perm:[2,3,0,1] row_mask:0xf bank_mask:0xf
	s_nop 1
	v_add_f32_dpp v47, v47, v47 row_half_mirror row_mask:0xf bank_mask:0xf
	s_nop 1
	v_add_f32_dpp v47, v47, v47 row_mirror row_mask:0xf bank_mask:0xf
	v_mov_b32_e32 v49, v47
	v_mov_b32_e32 v53, v47
	s_nop 1
	v_permlane16_swap_b32_e32 v49, v53
	s_nop 1
	v_add_f32_e32 v47, v49, v53
	v_mov_b32_e32 v49, v47
	v_mov_b32_e32 v53, v47
	s_nop 1
	v_permlane32_swap_b32_e32 v49, v53
	s_nop 1
	v_add_f32_e32 v47, v49, v53
	v_xor_b32_e32 v49, 2, v239
	v_cmp_lt_i32_e32 vcc, v49, v51
	s_nop 1
	v_cndmask_b32_e32 v49, v239, v49, vcc
	v_lshlrev_b32_e32 v49, 2, v49
	v_xor_b32_e32 v53, 4, v239
	v_cmp_lt_i32_e32 vcc, v53, v51
	s_nop 1
	v_cndmask_b32_e32 v53, v239, v53, vcc
	v_lshlrev_b32_e32 v53, 2, v53
	v_xor_b32_e32 v66, 8, v239
	v_cmp_lt_i32_e32 vcc, v66, v51
	s_nop 1
	v_cndmask_b32_e32 v66, v239, v66, vcc
	v_lshlrev_b32_e32 v70, 2, v66
	v_xor_b32_e32 v66, 16, v239
	v_cmp_lt_i32_e32 vcc, v66, v51
	s_nop 1
	v_cndmask_b32_e32 v66, v239, v66, vcc
	v_lshlrev_b32_e32 v71, 2, v66
	v_xor_b32_e32 v66, 32, v239
	v_cmp_lt_i32_e32 vcc, v66, v51
	s_nop 1
	v_cndmask_b32_e32 v51, v239, v66, vcc
	v_lshlrev_b32_e32 v72, 2, v51
	v_fmac_f32_e32 v64, 0xba800000, v47
	v_fmac_f32_e32 v65, 0xba800000, v47
	v_fmac_f32_e32 v59, 0xba800000, v47
	v_fmac_f32_e32 v58, 0xba800000, v47
	v_mov_b32_e32 v66, v59
	v_mov_b32_e32 v67, v65
	v_mov_b32_e32 v59, v64
	v_pk_mul_f32 v[68:69], v[66:67], v[66:67]
	v_pk_mul_f32 v[64:65], v[58:59], v[58:59]
	v_fmac_f32_e32 v62, 0xba800000, v47
	v_pk_mov_b32 v[74:75], v[64:65], v[68:69] op_sel:[1,0]
	v_mov_b32_e32 v65, v69
	v_pk_add_f32 v[64:65], v[74:75], v[64:65]
	v_fmac_f32_e32 v63, 0xba800000, v47
	v_fmac_f32_e32 v61, 0xba800000, v47
	v_pk_add_f32 v[68:69], v[64:65], v[64:65] op_sel_hi:[0,1]
	v_fmac_f32_e32 v60, 0xba800000, v47
	v_mov_b32_e32 v64, v61
	v_mov_b32_e32 v65, v63
	v_mov_b32_e32 v61, v62
	v_pk_mul_f32 v[74:75], v[64:65], v[64:65]
	v_pk_mul_f32 v[62:63], v[60:61], v[60:61]
	v_fmac_f32_e32 v54, 0xba800000, v47
	v_pk_mov_b32 v[76:77], v[62:63], v[74:75] op_sel:[1,0]
	v_mov_b32_e32 v63, v75
	v_pk_add_f32 v[62:63], v[76:77], v[62:63]
	v_fmac_f32_e32 v55, 0xba800000, v47
	v_pk_add_f32 v[62:63], v[62:63], v[62:63] op_sel_hi:[0,1]
	v_fmac_f32_e32 v56, 0xba800000, v47
	v_mul_f32_e32 v62, v54, v54
	v_fmac_f32_e32 v57, 0xba800000, v47
	v_pk_fma_f32 v[74:75], v[54:55], v[54:55], v[62:63] op_sel_hi:[1,1,0]
	v_mul_f32_e32 v62, v56, v56
	v_pk_fma_f32 v[76:77], v[56:57], v[56:57], v[62:63] op_sel_hi:[1,1,0]
	v_fmac_f32_e32 v48, 0xba800000, v47
	v_fmac_f32_e32 v46, 0xba800000, v47
	v_fmac_f32_e32 v52, 0xba800000, v47
	v_fmac_f32_e32 v50, 0xba800000, v47
	v_mul_f32_e32 v74, v50, v50
	v_mul_f32_e32 v76, v52, v52
	v_mul_f32_e32 v68, v46, v46
	v_mul_f32_e32 v62, v48, v48
	v_pk_add_f32 v[74:75], v[74:75], v[76:77]
	v_pk_add_f32 v[62:63], v[68:69], v[62:63]
	s_nop 0
	v_pk_add_f32 v[62:63], v[74:75], v[62:63]
	s_nop 0
	v_add_f32_e32 v47, v62, v63
	s_nop 1
	v_add_f32_dpp v47, v47, v47 quad_perm:[1,0,3,2] row_mask:0xf bank_mask:0xf
	s_nop 1
	v_add_f32_dpp v47, v47, v47 quad_perm:[2,3,0,1] row_mask:0xf bank_mask:0xf
	s_nop 1
; #define GAS __attribute__((address_space(1)))
; __device__ __forceinline__ unsigned pk2(float lo, float hi) { return f2bf(lo) | (f2bf(hi) << 16); }
; #define WSB(F, off) ((bf16*)(wsq((F).ws) + (off)))
; __device__ __forceinline__ void ln_rows(const Frame& F, int idx, bool final_out, int row_lo, int row_hi, int gw0, int NGW, bool comb = false) {
;     ...
;         const float mean = wave_sum(s) * (1.f / D); float s2 = 0.f;
; #pragma unroll
;         for (int j = 0; j < 4; ++j) { v[j] = v[j] - mean; s2 += (v[j].x * v[j].x + v[j].y * v[j].y) + (v[j].z * v[j].z + v[j].w * v[j].w); }
;         const float rstd = 1.f / sqrtf(wave_sum(s2) * (1.f / D) + LN_EPS);
; #pragma unroll
;         for (int j = 0; j < 4; ++j) v[j] = v[j] * rstd * gv[j] + bv[j];
;         if (!final_out) { GAS v4u* o = (GAS v4u*)(WSB(F, WS_HB) + (size_t)m * D) + tc.lane;
; #pragma unroll
;             for (int j = 0; j < 2; ++j) o[64 * j] = (v4u){pk2(v[2 * j].x, v[2 * j].y), pk2(v[2 * j].z, v[2 * j].w), pk2(v[2 * j + 1].x, v[2 * j + 1].y), pk2(v[2 * j + 1].z, v[2 * j + 1].w)}; }
	v_add_f32_dpp v47, v47, v47 row_half_mirror row_mask:0xf bank_mask:0xf
	s_nop 1
	v_add_f32_dpp v47, v47, v47 row_mirror row_mask:0xf bank_mask:0xf
	v_mov_b32_e32 v51, v47
	v_mov_b32_e32 v72, v47
	s_nop 1
	v_permlane16_swap_b32_e32 v51, v72
	s_nop 1
	v_add_f32_e32 v47, v51, v72
	v_mov_b32_e32 v51, v47
	v_mov_b32_e32 v72, v47
	s_nop 1
	v_permlane32_swap_b32_e32 v51, v72
	s_nop 1
	v_add_f32_e32 v47, v51, v72
	v_fmamk_f32 v47, v47, 0x3a800000, v235
	v_cmp_gt_f32_e32 vcc, s89, v47
	v_mul_f32_e32 v51, 0x4f800000, v47
	s_nop 0
	v_cndmask_b32_e32 v47, v47, v51, vcc
	v_sqrt_f32_e32 v51, v47
	s_nop 0
	v_add_u32_e32 v62, -1, v51
	v_fma_f32 v63, -v62, v51, v47
	v_cmp_ge_f32_e64 s[4:5], 0, v63
	v_add_u32_e32 v63, 1, v51
	s_nop 0
	v_cndmask_b32_e64 v62, v51, v62, s[4:5]
	v_fma_f32 v51, -v63, v51, v47
	v_cmp_lt_f32_e64 s[4:5], 0, v51
	s_nop 1
	v_cndmask_b32_e64 v51, v62, v63, s[4:5]
	v_mul_f32_e32 v62, 0x37800000, v51
	v_cndmask_b32_e32 v51, v51, v62, vcc
	v_cmp_class_f32_e32 vcc, v47, v236
	s_nop 1
	v_cndmask_b32_e32 v47, v51, v47, vcc
	v_div_scale_f32 v51, s[4:5], v47, v47, 1.0
	v_rcp_f32_e32 v62, v51
	s_nop 0
	v_fma_f32 v63, -v51, v62, 1.0
	v_fmac_f32_e32 v62, v63, v62
	v_div_scale_f32 v63, vcc, 1.0, v47, 1.0
	v_mul_f32_e32 v68, v63, v62
	v_fma_f32 v69, -v51, v68, v63
	v_fmac_f32_e32 v68, v69, v62
	v_fma_f32 v51, -v51, v68, v63
	v_div_fmas_f32 v51, v51, v62, v68
	v_div_fixup_f32 v68, v51, v47, 1.0
	v_pk_mul_f32 v[58:59], v[58:59], v[68:69] op_sel_hi:[1,0]
	v_mov_b32_e32 v47, v48
	v_pk_mul_f32 v[62:63], v[66:67], v[68:69] op_sel_hi:[1,0]
	v_pk_mul_f32 v[60:61], v[60:61], v[68:69] op_sel_hi:[1,0]
	v_pk_mul_f32 v[46:47], v[46:47], v[68:69] op_sel_hi:[1,0]
	v_pk_fma_f32 v[58:59], v[6:7], v[58:59], v[14:15]
	v_pk_fma_f32 v[66:67], v[20:21], v[46:47], v[28:29]
	v_pk_fma_f32 v[46:47], v[2:3], v[60:61], v[10:11]
	v_pk_fma_f32 v[60:61], v[8:9], v[62:63], v[16:17]
	v_lshl_add_u64 v[62:63], s[8:9], 0, v[44:45]
	v_bfe_u32 v44, v58, 16, 1
	v_add3_u32 v44, v58, v44, s72
	v_bfe_u32 v45, v59, 16, 1
	v_lshrrev_b32_e32 v44, 16, v44
	v_add3_u32 v45, v59, v45, s72
	v_and_or_b32 v44, v45, s88, v44
	v_bfe_u32 v45, v60, 16, 1
	v_add3_u32 v45, v60, v45, s72
	v_bfe_u32 v48, v61, 16, 1
	v_lshrrev_b32_e32 v45, 16, v45
	v_add3_u32 v48, v61, v48, s72
	v_and_or_b32 v45, v48, s88, v45
	v_bfe_u32 v48, v46, 16, 1
	v_pk_mul_f32 v[64:65], v[64:65], v[68:69] op_sel_hi:[1,0]
	v_add3_u32 v46, v46, v48, s72
	v_bfe_u32 v48, v47, 16, 1
	v_pk_fma_f32 v[64:65], v[4:5], v[64:65], v[12:13]
	v_lshrrev_b32_e32 v46, 16, v46
	v_add3_u32 v47, v47, v48, s72
	v_and_or_b32 v46, v47, s88, v46
	v_bfe_u32 v47, v64, 16, 1
	v_add3_u32 v47, v64, v47, s72
	v_bfe_u32 v48, v65, 16, 1
	v_pk_mul_f32 v[54:55], v[54:55], v[68:69] op_sel_hi:[1,0]
	v_lshrrev_b32_e32 v47, 16, v47
	v_add3_u32 v48, v65, v48, s72
	v_pk_fma_f32 v[54:55], v[22:23], v[54:55], v[30:31]
	v_and_or_b32 v47, v48, s88, v47
	global_store_dwordx4 v[62:63], v[44:47], off
	v_pk_mul_f32 v[56:57], v[56:57], v[68:69] op_sel_hi:[1,0]
	v_mov_b32_e32 v51, v52
	v_bfe_u32 v44, v54, 16, 1
	v_add3_u32 v44, v54, v44, s72
	v_bfe_u32 v45, v55, 16, 1
	v_pk_fma_f32 v[56:57], v[24:25], v[56:57], v[32:33]
	v_lshrrev_b32_e32 v44, 16, v44
	v_add3_u32 v45, v55, v45, s72
	v_and_or_b32 v44, v45, s88, v44
	v_bfe_u32 v45, v56, 16, 1
	v_pk_mul_f32 v[50:51], v[50:51], v[68:69] op_sel_hi:[1,0]
	v_add3_u32 v45, v56, v45, s72
	v_bfe_u32 v46, v57, 16, 1
	v_pk_fma_f32 v[50:51], v[18:19], v[50:51], v[26:27]
	v_lshrrev_b32_e32 v45, 16, v45
	v_add3_u32 v46, v57, v46, s72
	v_and_or_b32 v45, v46, s88, v45
	v_bfe_u32 v46, v50, 16, 1
	v_add3_u32 v46, v50, v46, s72
	v_bfe_u32 v47, v51, 16, 1
	v_lshrrev_b32_e32 v46, 16, v46
	v_add3_u32 v47, v51, v47, s72
	v_and_or_b32 v46, v47, s88, v46
	v_bfe_u32 v47, v66, 16, 1
	v_add3_u32 v47, v66, v47, s72
	v_bfe_u32 v48, v67, 16, 1
	v_lshrrev_b32_e32 v47, 16, v47
	v_add3_u32 v48, v67, v48, s72
	v_and_or_b32 v47, v48, s88, v47
	global_store_dwordx4 v[62:63], v[44:47], off offset:1024
	s_cbranch_scc1 .LBB0_295
	v_lshlrev_b32_e32 v57, 16, v35
	v_lshlrev_b32_e32 v56, 16, v34
	v_and_b32_e32 v35, 0xffff0000, v35
	v_and_b32_e32 v34, 0xffff0000, v34
	v_pk_add_f32 v[58:59], v[56:57], v[34:35]
	v_lshlrev_b32_e32 v50, 16, v41
	v_and_b32_e32 v54, 0xffff0000, v41
	v_add_f32_e32 v41, v58, v59
	v_lshlrev_b32_e32 v59, 16, v37
	v_lshlrev_b32_e32 v58, 16, v36
	v_and_b32_e32 v37, 0xffff0000, v37
	v_and_b32_e32 v36, 0xffff0000, v36
	v_pk_add_f32 v[60:61], v[58:59], v[36:37]
	v_lshlrev_b32_e32 v44, 16, v38
	v_and_b32_e32 v45, 0xffff0000, v38
	v_lshlrev_b32_e32 v38, 16, v39
	v_and_b32_e32 v39, 0xffff0000, v39
	v_pk_add_f32 v[60:61], v[60:61], v[60:61] op_sel_hi:[0,1]
	v_lshlrev_b32_e32 v46, 16, v40
	v_and_b32_e32 v40, 0xffff0000, v40
	v_add_f32_e32 v55, 0, v41
	v_add_f32_e32 v47, v44, v45
	v_add_f32_e32 v41, v38, v39
	v_mov_b32_e32 v51, v61
	v_pk_add_f32 v[62:63], v[46:47], v[40:41]
	v_pk_add_f32 v[60:61], v[50:51], v[54:55]
	s_ashr_i32 s7, s6, 31
	v_pk_add_f32 v[60:61], v[62:63], v[60:61]
	s_lshl_b64 s[6:7], s[6:7], 11
	v_add_f32_e32 v41, v60, v61
	s_nop 1
	v_add_f32_dpp v41, v41, v41 quad_perm:[1,0,3,2] row_mask:0xf bank_mask:0xf
	s_nop 1
	v_add_f32_dpp v41, v41, v41 quad_perm:[2,3,0,1] row_mask:0xf bank_mask:0xf
	s_nop 1
	v_add_f32_dpp v41, v41, v41 row_half_mirror row_mask:0xf bank_mask:0xf
	s_nop 1
	v_add_f32_dpp v41, v41, v41 row_mirror row_mask:0xf bank_mask:0xf
	v_mov_b32_e32 v47, v41
	v_mov_b32_e32 v72, v41
	s_nop 1
	v_permlane16_swap_b32_e32 v47, v72
	s_nop 1
	v_add_f32_e32 v41, v47, v72
	v_mov_b32_e32 v47, v41
	v_mov_b32_e32 v72, v41
	s_nop 1
	v_permlane32_swap_b32_e32 v47, v72
	s_nop 1
	v_add_f32_e32 v41, v47, v72
	v_fmac_f32_e32 v34, 0xba800000, v41
; #define GAS __attribute__((address_space(1)))
; __device__ __forceinline__ unsigned pk2(float lo, float hi) { return f2bf(lo) | (f2bf(hi) << 16); }
; #define WSB(F, off) ((bf16*)(wsq((F).ws) + (off)))
; __device__ __forceinline__ void ln_rows(const Frame& F, int idx, bool final_out, int row_lo, int row_hi, int gw0, int NGW, bool comb = false) {
;     ...
;         const float mean = wave_sum(s) * (1.f / D); float s2 = 0.f;
; #pragma unroll
;         for (int j = 0; j < 4; ++j) { v[j] = v[j] - mean; s2 += (v[j].x * v[j].x + v[j].y * v[j].y) + (v[j].z * v[j].z + v[j].w * v[j].w); }
;         const float rstd = 1.f / sqrtf(wave_sum(s2) * (1.f / D) + LN_EPS);
; #pragma unroll
;         for (int j = 0; j < 4; ++j) v[j] = v[j] * rstd * gv[j] + bv[j];
;         if (!final_out) { GAS v4u* o = (GAS v4u*)(WSB(F, WS_HB) + (size_t)m * D) + tc.lane;
; #pragma unroll
;             for (int j = 0; j < 2; ++j) o[64 * j] = (v4u){pk2(v[2 * j].x, v[2 * j].y), pk2(v[2 * j].z, v[2 * j].w), pk2(v[2 * j + 1].x, v[2 * j + 1].y), pk2(v[2 * j + 1].z, v[2 * j + 1].w)}; }
	v_fmac_f32_e32 v35, 0xba800000, v41
	v_fmac_f32_e32 v57, 0xba800000, v41
	v_fmac_f32_e32 v56, 0xba800000, v41
	v_mov_b32_e32 v60, v57
	v_mov_b32_e32 v61, v35
	v_mov_b32_e32 v57, v34
	v_pk_mul_f32 v[62:63], v[60:61], v[60:61]
	v_pk_mul_f32 v[34:35], v[56:57], v[56:57]
	v_fmac_f32_e32 v36, 0xba800000, v41
	v_pk_mov_b32 v[64:65], v[34:35], v[62:63] op_sel:[1,0]
	v_mov_b32_e32 v35, v63
	v_fmac_f32_e32 v37, 0xba800000, v41
	v_fmac_f32_e32 v59, 0xba800000, v41
	v_pk_add_f32 v[34:35], v[64:65], v[34:35]
	v_fmac_f32_e32 v58, 0xba800000, v41
	v_mov_b32_e32 v62, v59
	v_mov_b32_e32 v63, v37
	v_mov_b32_e32 v59, v36
	v_pk_add_f32 v[34:35], v[34:35], v[34:35] op_sel_hi:[0,1]
	v_pk_mul_f32 v[64:65], v[62:63], v[62:63]
	v_pk_mul_f32 v[36:37], v[58:59], v[58:59]
	v_fmac_f32_e32 v44, 0xba800000, v41
	v_pk_mov_b32 v[66:67], v[36:37], v[64:65] op_sel:[1,0]
	v_mov_b32_e32 v37, v65
	v_fmac_f32_e32 v45, 0xba800000, v41
	v_fmac_f32_e32 v38, 0xba800000, v41
	v_mul_f32_e32 v34, v44, v44
	v_pk_add_f32 v[36:37], v[66:67], v[36:37]
	v_fmac_f32_e32 v39, 0xba800000, v41
	v_pk_fma_f32 v[64:65], v[44:45], v[44:45], v[34:35] op_sel_hi:[1,1,0]
	v_mul_f32_e32 v34, v38, v38
	v_pk_add_f32 v[36:37], v[36:37], v[36:37] op_sel_hi:[0,1]
	v_pk_fma_f32 v[66:67], v[38:39], v[38:39], v[34:35] op_sel_hi:[1,1,0]
	v_fmac_f32_e32 v54, 0xba800000, v41
	v_fmac_f32_e32 v50, 0xba800000, v41
	v_fmac_f32_e32 v40, 0xba800000, v41
	v_fmac_f32_e32 v46, 0xba800000, v41
	v_mul_f32_e32 v64, v46, v46
	v_mul_f32_e32 v66, v40, v40
	v_mul_f32_e32 v34, v50, v50
	v_mul_f32_e32 v36, v54, v54
	v_pk_add_f32 v[64:65], v[64:65], v[66:67]
	v_pk_add_f32 v[34:35], v[34:35], v[36:37]
	v_mov_b32_e32 v47, v40
	v_pk_add_f32 v[34:35], v[64:65], v[34:35]
	v_mov_b32_e32 v51, v54
	v_add_f32_e32 v34, v34, v35
	s_nop 1
	v_add_f32_dpp v34, v34, v34 quad_perm:[1,0,3,2] row_mask:0xf bank_mask:0xf
	s_nop 1
	v_add_f32_dpp v34, v34, v34 quad_perm:[2,3,0,1] row_mask:0xf bank_mask:0xf
	s_nop 1
	v_add_f32_dpp v34, v34, v34 row_half_mirror row_mask:0xf bank_mask:0xf
	s_nop 1
	v_add_f32_dpp v34, v34, v34 row_mirror row_mask:0xf bank_mask:0xf
	v_mov_b32_e32 v72, v34
	v_mov_b32_e32 v71, v34
	s_nop 1
	v_permlane16_swap_b32_e32 v72, v71
	s_nop 1
	v_add_f32_e32 v34, v72, v71
	v_mov_b32_e32 v72, v34
	v_mov_b32_e32 v71, v34
	s_nop 1
	v_permlane32_swap_b32_e32 v72, v71
	s_nop 1
	v_add_f32_e32 v1, v72, v71
	v_fmamk_f32 v1, v1, 0x3a800000, v235
	v_mul_f32_e32 v34, 0x4f800000, v1
	v_cmp_gt_f32_e32 vcc, s89, v1
	s_nop 1
	v_cndmask_b32_e32 v1, v1, v34, vcc
	v_sqrt_f32_e32 v34, v1
	s_nop 0
	v_add_u32_e32 v35, -1, v34
	v_fma_f32 v36, -v35, v34, v1
	v_cmp_ge_f32_e64 s[4:5], 0, v36
	v_add_u32_e32 v36, 1, v34
	s_nop 0
	v_cndmask_b32_e64 v35, v34, v35, s[4:5]
	v_fma_f32 v34, -v36, v34, v1
	v_cmp_lt_f32_e64 s[4:5], 0, v34
	s_nop 1
	v_cndmask_b32_e64 v34, v35, v36, s[4:5]
	v_mul_f32_e32 v35, 0x37800000, v34
	v_cndmask_b32_e32 v34, v34, v35, vcc
	v_cmp_class_f32_e32 vcc, v1, v236
	s_nop 1
	v_cndmask_b32_e32 v1, v34, v1, vcc
	v_div_scale_f32 v34, s[4:5], v1, v1, 1.0
	v_rcp_f32_e32 v35, v34
	s_mov_b64 s[4:5], s[46:47]
	s_add_u32 s4, s4, s6
	v_fma_f32 v36, -v34, v35, 1.0
	v_fmac_f32_e32 v35, v36, v35
	v_div_scale_f32 v36, vcc, 1.0, v1, 1.0
	v_mul_f32_e32 v37, v36, v35
	v_fma_f32 v41, -v34, v37, v36
	v_fmac_f32_e32 v37, v41, v35
	v_fma_f32 v34, -v34, v37, v36
	v_div_fmas_f32 v34, v34, v35, v37
	v_div_fixup_f32 v34, v34, v1, 1.0
	v_pk_mul_f32 v[36:37], v[56:57], v[34:35] op_sel_hi:[1,0]
	v_pk_mul_f32 v[48:49], v[60:61], v[34:35] op_sel_hi:[1,0]
	v_pk_mul_f32 v[52:53], v[58:59], v[34:35] op_sel_hi:[1,0]
	v_pk_mul_f32 v[56:57], v[62:63], v[34:35] op_sel_hi:[1,0]
	v_pk_mul_f32 v[44:45], v[44:45], v[34:35] op_sel_hi:[1,0]
	v_pk_mul_f32 v[38:39], v[38:39], v[34:35] op_sel_hi:[1,0]
	v_pk_mul_f32 v[40:41], v[46:47], v[34:35] op_sel_hi:[1,0]
	v_pk_mul_f32 v[34:35], v[50:51], v[34:35] op_sel_hi:[1,0]
	v_pk_fma_f32 v[48:49], v[8:9], v[48:49], v[16:17]
	v_pk_fma_f32 v[46:47], v[20:21], v[34:35], v[28:29]
	v_pk_fma_f32 v[34:35], v[6:7], v[36:37], v[14:15]
	v_pk_fma_f32 v[52:53], v[2:3], v[52:53], v[10:11]
	v_bfe_u32 v1, v34, 16, 1
	v_add3_u32 v1, v34, v1, s72
	v_bfe_u32 v34, v35, 16, 1
	v_lshrrev_b32_e32 v1, 16, v1
	v_add3_u32 v34, v35, v34, s72
	v_and_or_b32 v34, v34, s88, v1
	v_bfe_u32 v1, v48, 16, 1
	v_add3_u32 v1, v48, v1, s72
	v_bfe_u32 v35, v49, 16, 1
	v_lshrrev_b32_e32 v1, 16, v1
	v_add3_u32 v35, v49, v35, s72
	v_and_or_b32 v35, v35, s88, v1
	v_bfe_u32 v1, v52, 16, 1
	v_add3_u32 v1, v52, v1, s72
	v_bfe_u32 v36, v53, 16, 1
	v_pk_fma_f32 v[50:51], v[4:5], v[56:57], v[12:13]
	s_addc_u32 s5, s5, s7
	v_lshrrev_b32_e32 v1, 16, v1
	v_add3_u32 v36, v53, v36, s72
	v_lshl_add_u64 v[54:55], v[42:43], 4, s[4:5]
	s_mov_b64 s[4:5], 0x8200000
	v_and_or_b32 v36, v36, s88, v1
	v_bfe_u32 v1, v50, 16, 1
	v_lshl_add_u64 v[56:57], v[54:55], 0, s[4:5]
	v_add3_u32 v1, v50, v1, s72
	v_bfe_u32 v37, v51, 16, 1
	s_mov_b32 s4, 0x8200000
	v_pk_fma_f32 v[44:45], v[22:23], v[44:45], v[30:31]
	v_lshrrev_b32_e32 v1, 16, v1
	v_add3_u32 v37, v51, v37, s72
	v_add_co_u32_e32 v48, vcc, s4, v54
	v_and_or_b32 v37, v37, s88, v1
	s_nop 0
	v_addc_co_u32_e32 v49, vcc, 0, v55, vcc
	v_bfe_u32 v1, v44, 16, 1
	global_store_dwordx4 v[48:49], v[34:37], off
	v_add3_u32 v1, v44, v1, s72
	v_pk_fma_f32 v[38:39], v[24:25], v[38:39], v[32:33]
	v_bfe_u32 v34, v45, 16, 1
	v_lshrrev_b32_e32 v1, 16, v1
	v_add3_u32 v34, v45, v34, s72
	v_and_or_b32 v34, v34, s88, v1
	v_bfe_u32 v1, v38, 16, 1
	v_add3_u32 v1, v38, v1, s72
	v_bfe_u32 v35, v39, 16, 1
	v_pk_fma_f32 v[40:41], v[18:19], v[40:41], v[26:27]
	v_lshrrev_b32_e32 v1, 16, v1
	v_add3_u32 v35, v39, v35, s72
	v_and_or_b32 v35, v35, s88, v1
	v_bfe_u32 v1, v40, 16, 1
	v_add3_u32 v1, v40, v1, s72
	v_bfe_u32 v36, v41, 16, 1
	v_lshrrev_b32_e32 v1, 16, v1
	v_add3_u32 v36, v41, v36, s72
	v_and_or_b32 v36, v36, s88, v1
	v_bfe_u32 v1, v46, 16, 1
	v_add3_u32 v1, v46, v1, s72
	v_bfe_u32 v37, v47, 16, 1
	v_lshrrev_b32_e32 v1, 16, v1
	v_add3_u32 v37, v47, v37, s72
	v_and_or_b32 v37, v37, s88, v1
	global_store_dwordx4 v[56:57], v[34:37], off offset:1024
	s_branch .LBB0_295

; #define GAS __attribute__((address_space(1)))
; #define WSB(F, off) ((bf16*)(wsq((F).ws) + (off)))
; __device__ __forceinline__ void ln_rows(const Frame& F, int idx, bool final_out, int row_lo, int row_hi, int gw0, int NGW, bool comb = false) {
;     ...
;     for (int m0 = row_lo + gw; m0 < row_hi; m0 += 2 * NGW) {
;         v4u w[2][2]; const bool two = m0 + NGW < row_hi;
; #pragma unroll
;         for (int r = 0; r < 2; ++r) { const int m = (r == 0 || two) ? m0 + r * NGW : m0; const GAS v4u* yr = (const GAS v4u*)(WSB(F, comb ? WS_HB : WS_YB) + (size_t)m * D) + tc.lane; w[r][0] = yr[0]; w[r][1] = yr[64]; }
; #pragma unroll
;         for (int r = 0; r < 2; ++r) { const int m = m0 + r * NGW; if (r == 1 && !two) break;
;         f32x4 v[4]; float s = 0.f;
; #pragma unroll
;         for (int j = 0; j < 2; ++j) { const v4u x = w[r][j]; v[2 * j] = (f32x4){bflo(x.x), bfhi(x.x), bflo(x.y), bfhi(x.y)}; v[2 * j + 1] = (f32x4){bflo(x.z), bfhi(x.z), bflo(x.w), bfhi(x.w)}; }
;         if (comb) {
;             const GAS f32x4* pa = (const GAS f32x4*)((const float*)WSB(F, WS_ACT) + (size_t)(m - MP) * D) + 2 * tc.lane; const GAS f32x4* pb = pa + (size_t)512 * D / 4;
; #pragma unroll
;             for (int j = 0; j < 2; ++j) { v[2 * j] = v[2 * j] * ALPHA + (pa[128 * j] + pb[128 * j]) * 0.5f; v[2 * j + 1] = v[2 * j + 1] * ALPHA + (pa[128 * j + 1] + pb[128 * j + 1]) * 0.5f; } }
; #pragma unroll
;         for (int j = 0; j < 4; ++j) s += (v[j].x + v[j].y) + (v[j].z + v[j].w);
;         const float mean = wave_sum(s) * (1.f / D); float s2 = 0.f;
.LBB0_361:
	v_readlane_b32 s5, v253, 7
	s_mov_b64 s[6:7], s[46:47]
	s_add_i32 s4, s5, s8
	s_add_u32 s6, s6, s2
	s_addc_u32 s7, s7, s3
	s_cmp_lt_i32 s4, 0x10200
	v_lshlrev_b64 v[46:47], 4, v[42:43]
	s_cselect_b32 s5, s5, 0
	v_lshl_add_u64 v[34:35], s[6:7], 0, v[46:47]
	s_add_i32 s6, s5, s8
	s_ashr_i32 s7, s6, 31
	s_mov_b64 s[10:11], s[46:47]
	s_lshl_b64 s[6:7], s[6:7], 11
	global_load_dwordx4 v[48:51], v[34:35], off
	global_load_dwordx4 v[52:55], v[34:35], off offset:1024
	s_add_u32 s6, s10, s6
	s_addc_u32 s7, s11, s7
	v_lshl_add_u64 v[34:35], s[6:7], 0, v[46:47]
	s_mov_b64 s[6:7], 0x8200000
	s_mov_b32 s5, 0x8200000
	v_lshl_add_u64 v[36:37], v[34:35], 0, s[6:7]
	v_add_co_u32_e32 v34, vcc, s5, v34
	s_add_i32 s10, s8, 0xffff0000
	s_nop 0
	v_addc_co_u32_e32 v35, vcc, 0, v35, vcc
	s_mov_b64 s[6:7], s[46:47]
	s_ashr_i32 s11, s10, 31
	global_load_dwordx4 v[38:41], v[34:35], off
	s_nop 0
	global_load_dwordx4 v[34:37], v[36:37], off offset:1024
	s_lshl_b64 s[10:11], s[10:11], 12
	s_add_u32 s6, s6, s10
	s_addc_u32 s7, s7, s11
	v_lshl_add_u64 v[84:85], v[44:45], 4, s[6:7]
	s_mov_b32 s5, 0x10300000
	s_mov_b64 s[6:7], 0x10300000
	v_add_co_u32_e32 v56, vcc, s5, v84
	v_lshl_add_u64 v[76:77], v[84:85], 0, s[6:7]
	s_mov_b64 s[6:7], 0x10500000
	v_addc_co_u32_e32 v57, vcc, 0, v85, vcc
	s_mov_b32 s5, 0x10500000
	v_lshl_add_u64 v[72:73], v[84:85], 0, s[6:7]
	v_add_co_u32_e32 v80, vcc, s5, v84
	s_mov_b64 s[6:7], 0x10500800
	s_nop 0
	v_addc_co_u32_e32 v81, vcc, 0, v85, vcc
	v_lshl_add_u64 v[84:85], v[84:85], 0, s[6:7]
	global_load_dwordx4 v[56:59], v[56:57], off
	s_nop 0
	global_load_dwordx4 v[60:63], v[80:81], off
	global_load_dwordx4 v[64:67], v[76:77], off offset:16
	global_load_dwordx4 v[68:71], v[76:77], off offset:2048
	s_nop 0
	global_load_dwordx4 v[72:75], v[72:73], off offset:16
	s_nop 0
	global_load_dwordx4 v[76:79], v[76:77], off offset:2064
	s_nop 0
	global_load_dwordx4 v[80:83], v[80:81], off offset:2048
	s_mov_b64 s[10:11], s[46:47]
	global_load_dwordx4 v[84:87], v[84:85], off offset:16
	s_waitcnt vmcnt(0)
	v_lshlrev_b32_e32 v88, 16, v48
	v_and_b32_e32 v89, 0xffff0000, v48
	v_lshlrev_b32_e32 v48, 16, v49
	v_and_b32_e32 v49, 0xffff0000, v49
	v_lshlrev_b32_e32 v90, 16, v50
	v_and_b32_e32 v91, 0xffff0000, v50
	v_lshlrev_b32_e32 v50, 16, v51
	v_and_b32_e32 v51, 0xffff0000, v51
	v_lshlrev_b32_e32 v92, 16, v52
	v_and_b32_e32 v93, 0xffff0000, v52
	v_lshlrev_b32_e32 v52, 16, v53
	v_and_b32_e32 v53, 0xffff0000, v53
	v_lshlrev_b32_e32 v94, 16, v54
	v_and_b32_e32 v95, 0xffff0000, v54
	v_lshlrev_b32_e32 v54, 16, v55
	v_and_b32_e32 v55, 0xffff0000, v55
	v_pk_add_f32 v[58:59], v[58:59], v[62:63]
	v_pk_add_f32 v[56:57], v[56:57], v[60:61]
	v_pk_mul_f32 v[58:59], v[58:59], 0.5 op_sel_hi:[1,0]
	v_pk_add_f32 v[60:61], v[66:67], v[74:75]
	v_pk_add_f32 v[62:63], v[64:65], v[72:73]
	v_pk_add_f32 v[64:65], v[70:71], v[82:83]
	v_pk_add_f32 v[66:67], v[68:69], v[80:81]
	v_pk_add_f32 v[68:69], v[78:79], v[86:87]
	v_pk_mul_f32 v[56:57], v[56:57], 0.5 op_sel_hi:[1,0]
	v_pk_mul_f32 v[60:61], v[60:61], 0.5 op_sel_hi:[1,0]
	v_pk_mul_f32 v[62:63], v[62:63], 0.5 op_sel_hi:[1,0]
	v_pk_mul_f32 v[64:65], v[64:65], 0.5 op_sel_hi:[1,0]
	v_pk_mul_f32 v[68:69], v[68:69], 0.5 op_sel_hi:[1,0]
	v_pk_fma_f32 v[48:49], v[48:49], s[96:97], v[58:59] op_sel_hi:[1,0,1]
	v_pk_fma_f32 v[72:73], v[88:89], s[96:97], v[56:57] op_sel_hi:[1,0,1]
	v_pk_fma_f32 v[62:63], v[90:91], s[96:97], v[62:63] op_sel_hi:[1,0,1]
	v_pk_fma_f32 v[50:51], v[50:51], s[96:97], v[60:61] op_sel_hi:[1,0,1]
	v_pk_add_f32 v[70:71], v[76:77], v[84:85]
	v_pk_fma_f32 v[52:53], v[52:53], s[96:97], v[64:65] op_sel_hi:[1,0,1]
	v_pk_fma_f32 v[64:65], v[54:55], s[96:97], v[68:69] op_sel_hi:[1,0,1]
	v_pk_mov_b32 v[54:55], v[72:73], v[48:49] op_sel:[1,0]
	v_mov_b32_e32 v56, v72
	v_mov_b32_e32 v57, v49
	v_pk_mov_b32 v[58:59], v[62:63], v[50:51] op_sel:[1,0]
	v_mov_b32_e32 v68, v62
	v_mov_b32_e32 v69, v51
	v_pk_mul_f32 v[66:67], v[66:67], 0.5 op_sel_hi:[1,0]
	v_pk_mul_f32 v[70:71], v[70:71], 0.5 op_sel_hi:[1,0]
	v_pk_add_f32 v[54:55], v[54:55], v[56:57]
	v_pk_add_f32 v[56:57], v[58:59], v[68:69]
	v_pk_fma_f32 v[60:61], v[92:93], s[96:97], v[66:67] op_sel_hi:[1,0,1]
	v_pk_fma_f32 v[66:67], v[94:95], s[96:97], v[70:71] op_sel_hi:[1,0,1]
	v_add_f32_e32 v1, v54, v55
	v_pk_add_f32 v[54:55], v[56:57], v[56:57] op_sel:[0,1] op_sel_hi:[1,0]
	v_add_f32_e32 v70, v60, v61
	v_add_f32_e32 v56, 0, v1
	v_add_f32_e32 v58, v52, v53
	v_mov_b32_e32 v57, v66
	v_mov_b32_e32 v55, v67
	v_mov_b32_e32 v71, v64
	v_mov_b32_e32 v59, v65
	v_and_b32_e32 v1, 64, v239
	v_pk_add_f32 v[54:55], v[56:57], v[54:55]
	v_pk_add_f32 v[56:57], v[70:71], v[58:59]
	v_add_u32_e32 v58, 64, v1
	v_xor_b32_e32 v1, 1, v239
	v_cmp_lt_i32_e32 vcc, v1, v58
	v_pk_add_f32 v[54:55], v[54:55], v[56:57]
	s_nop 0
	v_cndmask_b32_e32 v1, v239, v1, vcc
	v_add_f32_e32 v54, v54, v55
	v_lshlrev_b32_e32 v1, 2, v1
	s_nop 1
	v_add_f32_dpp v54, v54, v54 quad_perm:[1,0,3,2] row_mask:0xf bank_mask:0xf
	s_nop 1
	v_add_f32_dpp v54, v54, v54 quad_perm:[2,3,0,1] row_mask:0xf bank_mask:0xf
	s_nop 1
	v_add_f32_dpp v54, v54, v54 row_half_mirror row_mask:0xf bank_mask:0xf
	s_nop 1
	v_add_f32_dpp v54, v54, v54 row_mirror row_mask:0xf bank_mask:0xf
	v_mov_b32_e32 v55, v54
	v_mov_b32_e32 v56, v54
	s_nop 1
	v_permlane16_swap_b32_e32 v55, v56
	s_nop 1
	v_add_f32_e32 v54, v55, v56
	v_mov_b32_e32 v55, v54
	v_mov_b32_e32 v56, v54
	s_nop 1
	v_permlane32_swap_b32_e32 v55, v56
	s_nop 1
	v_add_f32_e32 v59, v55, v56
	v_xor_b32_e32 v54, 2, v239
	v_cmp_lt_i32_e32 vcc, v54, v58
	s_nop 1
	v_cndmask_b32_e32 v54, v239, v54, vcc
	v_lshlrev_b32_e32 v54, 2, v54
	v_xor_b32_e32 v55, 4, v239
	v_cmp_lt_i32_e32 vcc, v55, v58
	s_nop 1
; #define GAS __attribute__((address_space(1)))
; __device__ __forceinline__ unsigned pk2(float lo, float hi) { return f2bf(lo) | (f2bf(hi) << 16); }
; #define WSB(F, off) ((bf16*)(wsq((F).ws) + (off)))
; __device__ __forceinline__ void ln_rows(const Frame& F, int idx, bool final_out, int row_lo, int row_hi, int gw0, int NGW, bool comb = false) {
;     ...
;         const float mean = wave_sum(s) * (1.f / D); float s2 = 0.f;
; #pragma unroll
;         for (int j = 0; j < 4; ++j) { v[j] = v[j] - mean; s2 += (v[j].x * v[j].x + v[j].y * v[j].y) + (v[j].z * v[j].z + v[j].w * v[j].w); }
;         const float rstd = 1.f / sqrtf(wave_sum(s2) * (1.f / D) + LN_EPS);
; #pragma unroll
;         for (int j = 0; j < 4; ++j) v[j] = v[j] * rstd * gv[j] + bv[j];
;         if (!final_out) { GAS v4u* o = (GAS v4u*)(WSB(F, WS_HB) + (size_t)m * D) + tc.lane;
; #pragma unroll
;             for (int j = 0; j < 2; ++j) o[64 * j] = (v4u){pk2(v[2 * j].x, v[2 * j].y), pk2(v[2 * j].z, v[2 * j].w), pk2(v[2 * j + 1].x, v[2 * j + 1].y), pk2(v[2 * j + 1].z, v[2 * j + 1].w)}; }
	v_cndmask_b32_e32 v55, v239, v55, vcc
	v_lshlrev_b32_e32 v55, 2, v55
	v_xor_b32_e32 v56, 8, v239
	v_cmp_lt_i32_e32 vcc, v56, v58
	s_nop 1
	v_cndmask_b32_e32 v56, v239, v56, vcc
	v_lshlrev_b32_e32 v56, 2, v56
	v_xor_b32_e32 v57, 16, v239
	v_cmp_lt_i32_e32 vcc, v57, v58
	s_nop 1
	v_cndmask_b32_e32 v57, v239, v57, vcc
	v_lshlrev_b32_e32 v57, 2, v57
	v_xor_b32_e32 v68, 32, v239
	v_cmp_lt_i32_e32 vcc, v68, v58
	s_nop 1
	v_cndmask_b32_e32 v58, v239, v68, vcc
	v_lshlrev_b32_e32 v58, 2, v58
	v_fmamk_f32 v73, v59, 0xba800000, v73
	v_fmac_f32_e32 v72, 0xba800000, v59
	v_fmamk_f32 v49, v59, 0xba800000, v49
	v_fmac_f32_e32 v48, 0xba800000, v59
	v_pk_mul_f32 v[68:69], v[48:49], v[48:49]
	v_pk_mul_f32 v[70:71], v[72:73], v[72:73]
	v_fmamk_f32 v63, v59, 0xba800000, v63
	v_pk_mov_b32 v[74:75], v[70:71], v[68:69] op_sel:[1,0]
	v_mov_b32_e32 v71, v69
	v_pk_add_f32 v[68:69], v[74:75], v[70:71]
	v_fmac_f32_e32 v62, 0xba800000, v59
	v_fmamk_f32 v51, v59, 0xba800000, v51
	v_fmac_f32_e32 v50, 0xba800000, v59
	v_pk_add_f32 v[68:69], v[68:69], v[68:69] op_sel_hi:[0,1]
	v_pk_mul_f32 v[70:71], v[50:51], v[50:51]
	v_pk_mul_f32 v[74:75], v[62:63], v[62:63]
	v_fmac_f32_e32 v60, 0xba800000, v59
	v_pk_mov_b32 v[76:77], v[74:75], v[70:71] op_sel:[1,0]
	v_mov_b32_e32 v75, v71
	v_fmamk_f32 v61, v59, 0xba800000, v61
	v_fmac_f32_e32 v52, 0xba800000, v59
	v_mul_f32_e32 v68, v60, v60
	v_pk_add_f32 v[70:71], v[76:77], v[74:75]
	v_fmamk_f32 v53, v59, 0xba800000, v53
	v_pk_fma_f32 v[74:75], v[60:61], v[60:61], v[68:69] op_sel_hi:[1,1,0]
	v_mul_f32_e32 v68, v52, v52
	v_pk_add_f32 v[70:71], v[70:71], v[70:71] op_sel_hi:[0,1]
	v_pk_fma_f32 v[76:77], v[52:53], v[52:53], v[68:69] op_sel_hi:[1,1,0]
	v_fmamk_f32 v65, v59, 0xba800000, v65
	v_fmac_f32_e32 v64, 0xba800000, v59
	v_fmamk_f32 v67, v59, 0xba800000, v67
	v_fmac_f32_e32 v66, 0xba800000, v59
	v_mul_f32_e32 v74, v66, v66
	v_mul_f32_e32 v76, v67, v67
	v_mul_f32_e32 v68, v64, v64
	v_mul_f32_e32 v70, v65, v65
	v_pk_add_f32 v[74:75], v[74:75], v[76:77]
	v_pk_add_f32 v[68:69], v[68:69], v[70:71]
	s_nop 0
	v_pk_add_f32 v[68:69], v[74:75], v[68:69]
	s_nop 0
	v_add_f32_e32 v59, v68, v69
	s_nop 1
	v_add_f32_dpp v59, v59, v59 quad_perm:[1,0,3,2] row_mask:0xf bank_mask:0xf
	s_nop 1
	v_add_f32_dpp v59, v59, v59 quad_perm:[2,3,0,1] row_mask:0xf bank_mask:0xf
	s_nop 1
	v_add_f32_dpp v59, v59, v59 row_half_mirror row_mask:0xf bank_mask:0xf
	s_nop 1
	v_add_f32_dpp v59, v59, v59 row_mirror row_mask:0xf bank_mask:0xf
	v_mov_b32_e32 v68, v59
	v_mov_b32_e32 v58, v59
	s_nop 1
	v_permlane16_swap_b32_e32 v68, v58
	s_nop 1
	v_add_f32_e32 v59, v68, v58
	v_mov_b32_e32 v68, v59
	v_mov_b32_e32 v58, v59
	s_nop 1
	v_permlane32_swap_b32_e32 v68, v58
	s_nop 1
	v_add_f32_e32 v59, v68, v58
	v_fmamk_f32 v59, v59, 0x3a800000, v235
	v_mul_f32_e32 v68, 0x4f800000, v59
	v_cmp_gt_f32_e32 vcc, s89, v59
	s_nop 1
	v_cndmask_b32_e32 v59, v59, v68, vcc
	v_sqrt_f32_e32 v68, v59
	s_nop 0
	v_add_u32_e32 v69, -1, v68
	v_fma_f32 v70, -v69, v68, v59
	v_cmp_ge_f32_e64 s[6:7], 0, v70
	v_add_u32_e32 v70, 1, v68
	s_nop 0
	v_cndmask_b32_e64 v69, v68, v69, s[6:7]
	v_fma_f32 v68, -v70, v68, v59
	v_cmp_lt_f32_e64 s[6:7], 0, v68
	s_nop 1
	v_cndmask_b32_e64 v68, v69, v70, s[6:7]
	v_mul_f32_e32 v69, 0x37800000, v68
	v_cndmask_b32_e32 v68, v68, v69, vcc
	v_cmp_class_f32_e32 vcc, v59, v236
	s_nop 1
	v_cndmask_b32_e32 v59, v68, v59, vcc
	v_div_scale_f32 v68, s[6:7], v59, v59, 1.0
	v_rcp_f32_e32 v69, v68
	s_add_u32 s6, s10, s2
	s_addc_u32 s7, s11, s3
	s_cmp_gt_i32 s4, 0x101ff
	v_fma_f32 v70, -v68, v69, 1.0
	v_fmac_f32_e32 v69, v70, v69
	v_div_scale_f32 v70, vcc, 1.0, v59, 1.0
	v_mul_f32_e32 v71, v70, v69
	v_fma_f32 v74, -v68, v71, v70
	v_fmac_f32_e32 v71, v74, v69
	v_fma_f32 v68, -v68, v71, v70
	v_div_fmas_f32 v68, v68, v69, v71
	v_div_fixup_f32 v68, v68, v59, 1.0
	v_pk_mul_f32 v[70:71], v[72:73], v[68:69] op_sel_hi:[1,0]
	v_pk_mul_f32 v[48:49], v[48:49], v[68:69] op_sel_hi:[1,0]
	v_pk_mul_f32 v[62:63], v[62:63], v[68:69] op_sel_hi:[1,0]
	v_pk_mul_f32 v[50:51], v[50:51], v[68:69] op_sel_hi:[1,0]
	v_pk_mul_f32 v[60:61], v[60:61], v[68:69] op_sel_hi:[1,0]
	v_pk_mul_f32 v[52:53], v[52:53], v[68:69] op_sel_hi:[1,0]
	v_pk_mul_f32 v[66:67], v[66:67], v[68:69] op_sel_hi:[1,0]
	v_pk_mul_f32 v[64:65], v[64:65], v[68:69] op_sel_hi:[1,0]
	v_pk_fma_f32 v[68:69], v[6:7], v[70:71], v[14:15]
	v_lshl_add_u64 v[70:71], s[6:7], 0, v[46:47]
	v_bfe_u32 v46, v68, 16, 1
	v_add3_u32 v46, v68, v46, s72
	v_bfe_u32 v47, v69, 16, 1
	v_pk_fma_f32 v[48:49], v[8:9], v[48:49], v[16:17]
	v_lshrrev_b32_e32 v46, 16, v46
	v_add3_u32 v47, v69, v47, s72
	v_and_or_b32 v46, v47, s88, v46
	v_bfe_u32 v47, v48, 16, 1
	v_add3_u32 v47, v48, v47, s72
	v_bfe_u32 v48, v49, 16, 1
	v_pk_fma_f32 v[62:63], v[2:3], v[62:63], v[10:11]
	v_lshrrev_b32_e32 v47, 16, v47
	v_add3_u32 v48, v49, v48, s72
	v_and_or_b32 v47, v48, s88, v47
	v_bfe_u32 v48, v62, 16, 1
	v_add3_u32 v48, v62, v48, s72
	v_bfe_u32 v49, v63, 16, 1
	v_pk_fma_f32 v[50:51], v[4:5], v[50:51], v[12:13]
	v_lshrrev_b32_e32 v48, 16, v48
	v_add3_u32 v49, v63, v49, s72
	v_and_or_b32 v48, v49, s88, v48
	v_bfe_u32 v49, v50, 16, 1
	v_add3_u32 v49, v50, v49, s72
	v_bfe_u32 v50, v51, 16, 1
	v_lshrrev_b32_e32 v49, 16, v49
	v_add3_u32 v50, v51, v50, s72
	v_pk_fma_f32 v[60:61], v[22:23], v[60:61], v[30:31]
	v_and_or_b32 v49, v50, s88, v49
	global_store_dwordx4 v[70:71], v[46:49], off
	v_pk_fma_f32 v[52:53], v[24:25], v[52:53], v[32:33]
	v_pk_fma_f32 v[66:67], v[18:19], v[66:67], v[26:27]
	v_bfe_u32 v46, v60, 16, 1
	v_add3_u32 v46, v60, v46, s72
	v_bfe_u32 v47, v61, 16, 1
	v_lshrrev_b32_e32 v46, 16, v46
	v_add3_u32 v47, v61, v47, s72
	v_and_or_b32 v46, v47, s88, v46
	v_bfe_u32 v47, v52, 16, 1
	v_add3_u32 v47, v52, v47, s72
	v_bfe_u32 v48, v53, 16, 1
	v_lshrrev_b32_e32 v47, 16, v47
	v_add3_u32 v48, v53, v48, s72
	v_and_or_b32 v47, v48, s88, v47
	v_bfe_u32 v48, v66, 16, 1
	v_add3_u32 v48, v66, v48, s72
	v_bfe_u32 v49, v67, 16, 1
	v_pk_fma_f32 v[64:65], v[20:21], v[64:65], v[28:29]
	v_lshrrev_b32_e32 v48, 16, v48
	v_add3_u32 v49, v67, v49, s72
	v_and_or_b32 v48, v49, s88, v48
	v_bfe_u32 v49, v64, 16, 1
	v_add3_u32 v49, v64, v49, s72
	v_bfe_u32 v50, v65, 16, 1
	v_lshrrev_b32_e32 v49, 16, v49
	v_add3_u32 v50, v65, v50, s72
	v_and_or_b32 v49, v50, s88, v49
	global_store_dwordx4 v[70:71], v[46:49], off offset:1024
	s_cbranch_scc1 .LBB0_360
; #define GAS __attribute__((address_space(1)))
; #define WSB(F, off) ((bf16*)(wsq((F).ws) + (off)))
; __device__ __forceinline__ void ln_rows(const Frame& F, int idx, bool final_out, int row_lo, int row_hi, int gw0, int NGW, bool comb = false) {
;     ...
;         for (int r = 0; r < 2; ++r) { const int m = (r == 0 || two) ? m0 + r * NGW : m0; const GAS v4u* yr = (const GAS v4u*)(WSB(F, comb ? WS_HB : WS_YB) + (size_t)m * D) + tc.lane; w[r][0] = yr[0]; w[r][1] = yr[64]; }
; #pragma unroll
;         for (int r = 0; r < 2; ++r) { const int m = m0 + r * NGW; if (r == 1 && !two) break;
;         f32x4 v[4]; float s = 0.f;
; #pragma unroll
;         for (int j = 0; j < 2; ++j) { const v4u x = w[r][j]; v[2 * j] = (f32x4){bflo(x.x), bfhi(x.x), bflo(x.y), bfhi(x.y)}; v[2 * j + 1] = (f32x4){bflo(x.z), bfhi(x.z), bflo(x.w), bfhi(x.w)}; }
;         if (comb) {
;             const GAS f32x4* pa = (const GAS f32x4*)((const float*)WSB(F, WS_ACT) + (size_t)(m - MP) * D) + 2 * tc.lane; const GAS f32x4* pb = pa + (size_t)512 * D / 4;
; #pragma unroll
;             for (int j = 0; j < 2; ++j) { v[2 * j] = v[2 * j] * ALPHA + (pa[128 * j] + pb[128 * j]) * 0.5f; v[2 * j + 1] = v[2 * j + 1] * ALPHA + (pa[128 * j + 1] + pb[128 * j + 1]) * 0.5f; } }
; #pragma unroll
;         for (int j = 0; j < 4; ++j) s += (v[j].x + v[j].y) + (v[j].z + v[j].w);
;         const float mean = wave_sum(s) * (1.f / D); float s2 = 0.f;
	s_add_i32 s10, s4, 0xffff0000
	s_mov_b64 s[6:7], s[46:47]
	s_ashr_i32 s11, s10, 31
	s_lshl_b64 s[10:11], s[10:11], 12
	s_add_u32 s6, s6, s10
	s_addc_u32 s7, s7, s11
	v_lshl_add_u64 v[76:77], v[44:45], 4, s[6:7]
	s_mov_b32 s5, 0x10300000
	v_lshlrev_b32_e32 v72, 16, v34
	v_and_b32_e32 v73, 0xffff0000, v34
	v_add_co_u32_e32 v34, vcc, s5, v76
	v_lshlrev_b32_e32 v74, 16, v35
	v_and_b32_e32 v75, 0xffff0000, v35
	s_mov_b64 s[6:7], 0x10300000
	v_addc_co_u32_e32 v35, vcc, 0, v77, vcc
	s_mov_b32 s5, 0x10500000
	v_lshl_add_u64 v[78:79], v[76:77], 0, s[6:7]
	s_mov_b64 s[6:7], 0x10500000
	v_add_co_u32_e32 v80, vcc, s5, v76
	v_lshl_add_u64 v[60:61], v[76:77], 0, s[6:7]
	s_nop 0
	v_addc_co_u32_e32 v81, vcc, 0, v77, vcc
	v_lshlrev_b32_e32 v64, 16, v38
	v_and_b32_e32 v65, 0xffff0000, v38
	v_lshlrev_b32_e32 v66, 16, v39
	v_and_b32_e32 v67, 0xffff0000, v39
	v_lshlrev_b32_e32 v68, 16, v40
	v_and_b32_e32 v69, 0xffff0000, v40
	v_lshlrev_b32_e32 v70, 16, v41
	v_and_b32_e32 v71, 0xffff0000, v41
	v_lshlrev_b32_e32 v50, 16, v36
	v_and_b32_e32 v51, 0xffff0000, v36
	v_lshlrev_b32_e32 v52, 16, v37
	v_and_b32_e32 v53, 0xffff0000, v37
	global_load_dwordx4 v[34:37], v[34:35], off
	s_nop 0
	global_load_dwordx4 v[38:41], v[78:79], off offset:16
	global_load_dwordx4 v[46:49], v[80:81], off
	s_nop 0
	global_load_dwordx4 v[60:63], v[60:61], off offset:16
	s_mov_b64 s[6:7], 0x10500800
	s_ashr_i32 s5, s4, 31
	s_lshl_b64 s[4:5], s[4:5], 11
	s_waitcnt vmcnt(1)
	v_pk_add_f32 v[36:37], v[36:37], v[48:49]
	v_pk_add_f32 v[34:35], v[34:35], v[46:47]
	v_pk_mul_f32 v[36:37], v[36:37], 0.5 op_sel_hi:[1,0]
	v_pk_mul_f32 v[46:47], v[34:35], 0.5 op_sel_hi:[1,0]
	s_waitcnt vmcnt(0)
	v_pk_add_f32 v[40:41], v[40:41], v[62:63]
	v_pk_add_f32 v[38:39], v[38:39], v[60:61]
	v_pk_fma_f32 v[34:35], v[66:67], s[96:97], v[36:37] op_sel_hi:[1,0,1]
	v_pk_fma_f32 v[36:37], v[64:65], s[96:97], v[46:47] op_sel_hi:[1,0,1]
	v_pk_mul_f32 v[40:41], v[40:41], 0.5 op_sel_hi:[1,0]
	v_pk_mul_f32 v[46:47], v[38:39], 0.5 op_sel_hi:[1,0]
	v_pk_fma_f32 v[38:39], v[70:71], s[96:97], v[40:41] op_sel_hi:[1,0,1]
	v_pk_fma_f32 v[40:41], v[68:69], s[96:97], v[46:47] op_sel_hi:[1,0,1]
	v_lshl_add_u64 v[68:69], v[76:77], 0, s[6:7]
	global_load_dwordx4 v[60:63], v[78:79], off offset:2064
	global_load_dwordx4 v[46:49], v[78:79], off offset:2048
	global_load_dwordx4 v[64:67], v[80:81], off offset:2048
	s_nop 0
	global_load_dwordx4 v[68:71], v[68:69], off offset:16
	s_waitcnt vmcnt(1)
	v_pk_add_f32 v[48:49], v[48:49], v[66:67]
	s_waitcnt vmcnt(0)
	v_pk_add_f32 v[62:63], v[62:63], v[70:71]
	v_pk_add_f32 v[60:61], v[60:61], v[68:69]
	v_pk_add_f32 v[46:47], v[46:47], v[64:65]
	v_pk_mul_f32 v[62:63], v[62:63], 0.5 op_sel_hi:[1,0]
	v_pk_mul_f32 v[60:61], v[60:61], 0.5 op_sel_hi:[1,0]
	v_pk_mul_f32 v[48:49], v[48:49], 0.5 op_sel_hi:[1,0]
	v_pk_mul_f32 v[64:65], v[46:47], 0.5 op_sel_hi:[1,0]
	v_pk_fma_f32 v[52:53], v[52:53], s[96:97], v[62:63] op_sel_hi:[1,0,1]
	v_pk_fma_f32 v[50:51], v[50:51], s[96:97], v[60:61] op_sel_hi:[1,0,1]
	v_pk_mov_b32 v[60:61], v[36:37], v[34:35] op_sel:[1,0]
	v_mov_b32_e32 v62, v36
	v_mov_b32_e32 v63, v35
	v_pk_fma_f32 v[46:47], v[74:75], s[96:97], v[48:49] op_sel_hi:[1,0,1]
	v_pk_fma_f32 v[48:49], v[72:73], s[96:97], v[64:65] op_sel_hi:[1,0,1]
	v_pk_add_f32 v[60:61], v[60:61], v[62:63]
	v_pk_mov_b32 v[62:63], v[40:41], v[38:39] op_sel:[1,0]
	v_mov_b32_e32 v64, v40
	v_mov_b32_e32 v65, v39
	v_pk_add_f32 v[62:63], v[62:63], v[64:65]
	v_add_f32_e32 v59, v60, v61
	v_pk_add_f32 v[62:63], v[62:63], v[62:63] op_sel:[0,1] op_sel_hi:[1,0]
	v_add_f32_e32 v60, 0, v59
	v_add_f32_e32 v64, v48, v49
	v_add_f32_e32 v66, v46, v47
	v_mov_b32_e32 v61, v50
	v_mov_b32_e32 v63, v51
	v_mov_b32_e32 v65, v52
	v_mov_b32_e32 v67, v53
	v_pk_add_f32 v[60:61], v[60:61], v[62:63]
	v_pk_add_f32 v[62:63], v[64:65], v[66:67]
	s_nop 0
	v_pk_add_f32 v[60:61], v[60:61], v[62:63]
	s_nop 0
	v_add_f32_e32 v59, v60, v61
	s_nop 1
	v_add_f32_dpp v59, v59, v59 quad_perm:[1,0,3,2] row_mask:0xf bank_mask:0xf
	s_nop 1
	v_add_f32_dpp v59, v59, v59 quad_perm:[2,3,0,1] row_mask:0xf bank_mask:0xf
	s_nop 1
	v_add_f32_dpp v59, v59, v59 row_half_mirror row_mask:0xf bank_mask:0xf
	s_nop 1
	v_add_f32_dpp v59, v59, v59 row_mirror row_mask:0xf bank_mask:0xf
	v_mov_b32_e32 v60, v59
	v_mov_b32_e32 v58, v59
	s_nop 1
	v_permlane16_swap_b32_e32 v60, v58
	s_nop 1
	v_add_f32_e32 v59, v60, v58
	v_mov_b32_e32 v60, v59
	v_mov_b32_e32 v58, v59
	s_nop 1
	v_permlane32_swap_b32_e32 v60, v58
	s_nop 1
	v_add_f32_e32 v59, v60, v58
	v_fmamk_f32 v37, v59, 0xba800000, v37
	v_fmac_f32_e32 v36, 0xba800000, v59
	v_fmamk_f32 v35, v59, 0xba800000, v35
	v_fmac_f32_e32 v34, 0xba800000, v59
	v_pk_mul_f32 v[60:61], v[34:35], v[34:35]
	v_pk_mul_f32 v[62:63], v[36:37], v[36:37]
	v_fmamk_f32 v41, v59, 0xba800000, v41
	v_pk_mov_b32 v[64:65], v[62:63], v[60:61] op_sel:[1,0]
	v_mov_b32_e32 v63, v61
	v_pk_add_f32 v[60:61], v[64:65], v[62:63]
	v_fmac_f32_e32 v40, 0xba800000, v59
	v_fmamk_f32 v39, v59, 0xba800000, v39
	v_fmac_f32_e32 v38, 0xba800000, v59
	v_pk_add_f32 v[60:61], v[60:61], v[60:61] op_sel_hi:[0,1]
	v_pk_mul_f32 v[62:63], v[38:39], v[38:39]
	v_pk_mul_f32 v[64:65], v[40:41], v[40:41]
	v_fmac_f32_e32 v48, 0xba800000, v59
; #define GAS __attribute__((address_space(1)))
; __device__ __forceinline__ unsigned pk2(float lo, float hi) { return f2bf(lo) | (f2bf(hi) << 16); }
; #define WSB(F, off) ((bf16*)(wsq((F).ws) + (off)))
; __device__ __forceinline__ void ln_rows(const Frame& F, int idx, bool final_out, int row_lo, int row_hi, int gw0, int NGW, bool comb = false) {
;     ...
;         const float mean = wave_sum(s) * (1.f / D); float s2 = 0.f;
; #pragma unroll
;         for (int j = 0; j < 4; ++j) { v[j] = v[j] - mean; s2 += (v[j].x * v[j].x + v[j].y * v[j].y) + (v[j].z * v[j].z + v[j].w * v[j].w); }
;         const float rstd = 1.f / sqrtf(wave_sum(s2) * (1.f / D) + LN_EPS);
; #pragma unroll
;         for (int j = 0; j < 4; ++j) v[j] = v[j] * rstd * gv[j] + bv[j];
;         if (!final_out) { GAS v4u* o = (GAS v4u*)(WSB(F, WS_HB) + (size_t)m * D) + tc.lane;
; #pragma unroll
;             for (int j = 0; j < 2; ++j) o[64 * j] = (v4u){pk2(v[2 * j].x, v[2 * j].y), pk2(v[2 * j].z, v[2 * j].w), pk2(v[2 * j + 1].x, v[2 * j + 1].y), pk2(v[2 * j + 1].z, v[2 * j + 1].w)}; }
	v_pk_mov_b32 v[66:67], v[64:65], v[62:63] op_sel:[1,0]
	v_mov_b32_e32 v65, v63
	v_fmamk_f32 v49, v59, 0xba800000, v49
	v_fmac_f32_e32 v46, 0xba800000, v59
	v_mul_f32_e32 v60, v48, v48
	v_pk_add_f32 v[62:63], v[66:67], v[64:65]
	v_fmamk_f32 v47, v59, 0xba800000, v47
	v_pk_fma_f32 v[64:65], v[48:49], v[48:49], v[60:61] op_sel_hi:[1,1,0]
	v_mul_f32_e32 v60, v46, v46
	v_pk_add_f32 v[62:63], v[62:63], v[62:63] op_sel_hi:[0,1]
	v_pk_fma_f32 v[66:67], v[46:47], v[46:47], v[60:61] op_sel_hi:[1,1,0]
	v_fmamk_f32 v53, v59, 0xba800000, v53
	v_fmac_f32_e32 v52, 0xba800000, v59
	v_fmamk_f32 v51, v59, 0xba800000, v51
	v_fmac_f32_e32 v50, 0xba800000, v59
	v_mul_f32_e32 v64, v50, v50
	v_mul_f32_e32 v66, v51, v51
	v_mul_f32_e32 v60, v52, v52
	v_mul_f32_e32 v62, v53, v53
	v_pk_add_f32 v[64:65], v[64:65], v[66:67]
	v_pk_add_f32 v[60:61], v[60:61], v[62:63]
	s_nop 0
	v_pk_add_f32 v[60:61], v[64:65], v[60:61]
	s_nop 0
	v_add_f32_e32 v59, v60, v61
	s_nop 1
	v_add_f32_dpp v59, v59, v59 quad_perm:[1,0,3,2] row_mask:0xf bank_mask:0xf
	s_nop 1
	v_add_f32_dpp v59, v59, v59 quad_perm:[2,3,0,1] row_mask:0xf bank_mask:0xf
	s_nop 1
	v_add_f32_dpp v59, v59, v59 row_half_mirror row_mask:0xf bank_mask:0xf
	s_nop 1
	v_add_f32_dpp v59, v59, v59 row_mirror row_mask:0xf bank_mask:0xf
	v_mov_b32_e32 v54, v59
	v_mov_b32_e32 v58, v59
	s_nop 1
	v_permlane16_swap_b32_e32 v54, v58
	s_nop 1
	v_add_f32_e32 v59, v54, v58
	v_mov_b32_e32 v54, v59
	v_mov_b32_e32 v58, v59
	s_nop 1
	v_permlane32_swap_b32_e32 v54, v58
	s_nop 1
	v_add_f32_e32 v1, v54, v58
	v_fmamk_f32 v1, v1, 0x3a800000, v235
	v_cmp_gt_f32_e32 vcc, s89, v1
	v_mul_f32_e32 v54, 0x4f800000, v1
	s_nop 0
	v_cndmask_b32_e32 v1, v1, v54, vcc
	v_sqrt_f32_e32 v54, v1
	s_nop 0
	v_add_u32_e32 v55, -1, v54
	v_fma_f32 v56, -v55, v54, v1
	v_cmp_ge_f32_e64 s[6:7], 0, v56
	v_add_u32_e32 v56, 1, v54
	s_nop 0
	v_cndmask_b32_e64 v55, v54, v55, s[6:7]
	v_fma_f32 v54, -v56, v54, v1
	v_cmp_lt_f32_e64 s[6:7], 0, v54
	s_nop 1
	v_cndmask_b32_e64 v54, v55, v56, s[6:7]
	v_mul_f32_e32 v55, 0x37800000, v54
	v_cndmask_b32_e32 v54, v54, v55, vcc
	v_cmp_class_f32_e32 vcc, v1, v236
	s_nop 1
	v_cndmask_b32_e32 v1, v54, v1, vcc
	v_div_scale_f32 v54, s[6:7], v1, v1, 1.0
	v_rcp_f32_e32 v55, v54
	s_mov_b64 s[6:7], s[46:47]
	s_add_u32 s4, s6, s4
	v_fma_f32 v56, -v54, v55, 1.0
	v_fmac_f32_e32 v55, v56, v55
	v_div_scale_f32 v56, vcc, 1.0, v1, 1.0
	v_mul_f32_e32 v57, v56, v55
	v_fma_f32 v58, -v54, v57, v56
	v_fmac_f32_e32 v57, v58, v55
	v_fma_f32 v54, -v54, v57, v56
	v_div_fmas_f32 v54, v54, v55, v57
	v_div_fixup_f32 v54, v54, v1, 1.0
	v_pk_mul_f32 v[56:57], v[36:37], v[54:55] op_sel_hi:[1,0]
	v_pk_mul_f32 v[58:59], v[34:35], v[54:55] op_sel_hi:[1,0]
	v_pk_mul_f32 v[34:35], v[52:53], v[54:55] op_sel_hi:[1,0]
	v_pk_fma_f32 v[52:53], v[6:7], v[56:57], v[14:15]
	v_pk_mul_f32 v[36:37], v[50:51], v[54:55] op_sel_hi:[1,0]
	v_bfe_u32 v1, v52, 16, 1
	v_add3_u32 v1, v52, v1, s72
	v_bfe_u32 v52, v53, 16, 1
	v_pk_fma_f32 v[50:51], v[8:9], v[58:59], v[16:17]
	v_lshrrev_b32_e32 v1, 16, v1
	v_add3_u32 v52, v53, v52, s72
	v_and_or_b32 v52, v52, s88, v1
	v_bfe_u32 v1, v50, 16, 1
	v_pk_mul_f32 v[60:61], v[40:41], v[54:55] op_sel_hi:[1,0]
	v_add3_u32 v1, v50, v1, s72
	v_bfe_u32 v50, v51, 16, 1
	v_pk_mul_f32 v[40:41], v[48:49], v[54:55] op_sel_hi:[1,0]
	v_pk_fma_f32 v[48:49], v[2:3], v[60:61], v[10:11]
	v_lshrrev_b32_e32 v1, 16, v1
	v_add3_u32 v50, v51, v50, s72
	v_and_or_b32 v53, v50, s88, v1
	v_bfe_u32 v1, v48, 16, 1
	v_pk_mul_f32 v[62:63], v[38:39], v[54:55] op_sel_hi:[1,0]
	v_add3_u32 v1, v48, v1, s72
	v_bfe_u32 v48, v49, 16, 1
	v_pk_mul_f32 v[38:39], v[46:47], v[54:55] op_sel_hi:[1,0]
	v_pk_fma_f32 v[46:47], v[4:5], v[62:63], v[12:13]
	v_lshrrev_b32_e32 v1, 16, v1
	v_add3_u32 v48, v49, v48, s72
	v_and_or_b32 v54, v48, s88, v1
	v_bfe_u32 v1, v46, 16, 1
	s_addc_u32 s5, s7, s5
	v_add3_u32 v1, v46, v1, s72
	v_bfe_u32 v46, v47, 16, 1
	v_pk_fma_f32 v[40:41], v[22:23], v[40:41], v[30:31]
	v_lshl_add_u64 v[56:57], v[42:43], 4, s[4:5]
	s_mov_b64 s[4:5], 0x8200000
	v_lshrrev_b32_e32 v1, 16, v1
	v_add3_u32 v46, v47, v46, s72
	v_lshl_add_u64 v[58:59], v[56:57], 0, s[4:5]
	v_and_or_b32 v55, v46, s88, v1
	s_mov_b32 s4, 0x8200000
	v_bfe_u32 v1, v40, 16, 1
	v_add_co_u32_e32 v46, vcc, s4, v56
	v_add3_u32 v1, v40, v1, s72
	v_bfe_u32 v40, v41, 16, 1
	v_pk_fma_f32 v[38:39], v[24:25], v[38:39], v[32:33]
	v_addc_co_u32_e32 v47, vcc, 0, v57, vcc
	v_lshrrev_b32_e32 v1, 16, v1
	v_add3_u32 v40, v41, v40, s72
	global_store_dwordx4 v[46:47], v[52:55], off
	v_and_or_b32 v46, v40, s88, v1
	v_bfe_u32 v1, v38, 16, 1
	v_add3_u32 v1, v38, v1, s72
	v_bfe_u32 v38, v39, 16, 1
	v_pk_fma_f32 v[36:37], v[18:19], v[36:37], v[26:27]
	v_lshrrev_b32_e32 v1, 16, v1
	v_add3_u32 v38, v39, v38, s72
	v_and_or_b32 v47, v38, s88, v1
	v_bfe_u32 v1, v36, 16, 1
	v_add3_u32 v1, v36, v1, s72
	v_bfe_u32 v36, v37, 16, 1
	v_pk_fma_f32 v[34:35], v[20:21], v[34:35], v[28:29]
	v_lshrrev_b32_e32 v1, 16, v1
	v_add3_u32 v36, v37, v36, s72
	v_and_or_b32 v48, v36, s88, v1
	v_bfe_u32 v1, v34, 16, 1
	v_add3_u32 v1, v34, v1, s72
	v_bfe_u32 v34, v35, 16, 1
	v_lshrrev_b32_e32 v1, 16, v1
	v_add3_u32 v34, v35, v34, s72
	v_and_or_b32 v49, v34, s88, v1
	global_store_dwordx4 v[58:59], v[46:49], off offset:1024
	s_branch .LBB0_360

; #define GAS __attribute__((address_space(1)))
; #define WSB(F, off) ((bf16*)(wsq((F).ws) + (off)))
; __device__ __forceinline__ void ln_rows(const Frame& F, int idx, bool final_out, int row_lo, int row_hi, int gw0, int NGW, bool comb = false) {
;     ...
;     for (int m0 = row_lo + gw; m0 < row_hi; m0 += 2 * NGW) {
;         v4u w[2][2]; const bool two = m0 + NGW < row_hi;
; #pragma unroll
;         for (int r = 0; r < 2; ++r) { const int m = (r == 0 || two) ? m0 + r * NGW : m0; const GAS v4u* yr = (const GAS v4u*)(WSB(F, comb ? WS_HB : WS_YB) + (size_t)m * D) + tc.lane; w[r][0] = yr[0]; w[r][1] = yr[64]; }
; #pragma unroll
;         for (int r = 0; r < 2; ++r) { const int m = m0 + r * NGW; if (r == 1 && !two) break;
;         f32x4 v[4]; float s = 0.f;
; #pragma unroll
;         for (int j = 0; j < 2; ++j) { const v4u x = w[r][j]; v[2 * j] = (f32x4){bflo(x.x), bfhi(x.x), bflo(x.y), bfhi(x.y)}; v[2 * j + 1] = (f32x4){bflo(x.z), bfhi(x.z), bflo(x.w), bfhi(x.w)}; }
;         if (comb) {
;             const GAS f32x4* pa = (const GAS f32x4*)((const float*)WSB(F, WS_ACT) + (size_t)(m - MP) * D) + 2 * tc.lane; const GAS f32x4* pb = pa + (size_t)512 * D / 4;
; #pragma unroll
;             for (int j = 0; j < 2; ++j) { v[2 * j] = v[2 * j] * ALPHA + (pa[128 * j] + pb[128 * j]) * 0.5f; v[2 * j + 1] = v[2 * j + 1] * ALPHA + (pa[128 * j + 1] + pb[128 * j + 1]) * 0.5f; } }
; #pragma unroll
;         for (int j = 0; j < 4; ++j) s += (v[j].x + v[j].y) + (v[j].z + v[j].w);
;         const float mean = wave_sum(s) * (1.f / D); float s2 = 0.f;
; #pragma unroll
;         for (int j = 0; j < 4; ++j) { v[j] = v[j] - mean; s2 += (v[j].x * v[j].x + v[j].y * v[j].y) + (v[j].z * v[j].z + v[j].w * v[j].w); }
;         const float rstd = 1.f / sqrtf(wave_sum(s2) * (1.f / D) + LN_EPS);
.LBB0_1467:
	s_mov_b64 s[8:9], s[46:47]
	s_add_i32 s12, s10, 8
	s_add_u32 s8, s8, s11
	s_addc_u32 s9, s9, s18
	v_lshlrev_b64 v[44:45], 4, v[42:43]
	s_waitcnt vmcnt(3)
	v_lshl_add_u64 v[34:35], s[8:9], 0, v[44:45]
	s_mov_b32 s8, 0xf7f00000
	s_mov_b32 s9, -1
	v_lshl_add_u64 v[36:37], v[34:35], 0, s[8:9]
	v_add_co_u32_e32 v34, vcc, 0xf7f00000, v34
	s_cmp_lt_i32 s12, s2
	s_nop 0
	v_addc_co_u32_e32 v35, vcc, -1, v35, vcc
	global_load_dwordx4 v[60:63], v[34:35], off
	global_load_dwordx4 v[46:49], v[36:37], off offset:1024
	s_cselect_b32 s8, 8, 0
	s_add_i32 s8, s8, s10
	s_ashr_i32 s9, s8, 31
	s_mov_b64 s[16:17], s[46:47]
	s_lshl_b64 s[8:9], s[8:9], 11
	s_add_u32 s8, s16, s8
	s_addc_u32 s9, s17, s9
	v_lshl_add_u64 v[34:35], s[8:9], 0, v[44:45]
	s_mov_b64 s[8:9], 0x100000
	s_waitcnt vmcnt(4)
	v_lshl_add_u64 v[38:39], v[34:35], 0, s[8:9]
	s_mov_b32 s8, 0x100000
	v_add_co_u32_e32 v34, vcc, s8, v34
	s_mov_b64 s[8:9], s[46:47]
	s_nop 0
	v_addc_co_u32_e32 v35, vcc, 0, v35, vcc
	global_load_dwordx4 v[34:37], v[34:35], off
	s_nop 0
	global_load_dwordx4 v[38:41], v[38:39], off offset:1024
	s_add_u32 s16, s8, s11
	s_addc_u32 s17, s9, s18
	s_cmp_ge_i32 s12, s2
	s_waitcnt vmcnt(3)
	v_lshlrev_b32_e32 v59, 16, v61
	v_lshlrev_b32_e32 v58, 16, v60
	v_and_b32_e32 v65, 0xffff0000, v61
	v_and_b32_e32 v64, 0xffff0000, v60
	v_pk_add_f32 v[60:61], v[58:59], v[64:65]
	s_waitcnt vmcnt(2)
	v_lshlrev_b32_e32 v54, 16, v46
	v_add_f32_e32 v1, v60, v61
	v_lshlrev_b32_e32 v61, 16, v63
	v_lshlrev_b32_e32 v60, 16, v62
	v_and_b32_e32 v63, 0xffff0000, v63
	v_and_b32_e32 v62, 0xffff0000, v62
	v_and_b32_e32 v55, 0xffff0000, v46
	v_lshlrev_b32_e32 v56, 16, v47
	v_and_b32_e32 v57, 0xffff0000, v47
	v_pk_add_f32 v[66:67], v[60:61], v[62:63]
	v_lshlrev_b32_e32 v50, 16, v48
	v_and_b32_e32 v52, 0xffff0000, v48
	v_lshlrev_b32_e32 v46, 16, v49
	v_and_b32_e32 v48, 0xffff0000, v49
	v_add_f32_e32 v49, 0, v1
	v_pk_add_f32 v[66:67], v[66:67], v[66:67] op_sel_hi:[0,1]
	v_add_f32_e32 v51, v54, v55
	v_add_f32_e32 v53, v56, v57
	v_and_b32_e32 v1, 64, v239
	v_pk_add_f32 v[68:69], v[50:51], v[52:53]
	v_mov_b32_e32 v47, v67
	v_add_u32_e32 v51, 64, v1
	v_xor_b32_e32 v1, 1, v239
	v_pk_add_f32 v[66:67], v[46:47], v[48:49]
	v_cmp_lt_i32_e32 vcc, v1, v51
	v_pk_add_f32 v[66:67], v[68:69], v[66:67]
	s_nop 0
	v_cndmask_b32_e32 v1, v239, v1, vcc
	v_add_f32_e32 v47, v66, v67
	v_lshlrev_b32_e32 v1, 2, v1
	s_nop 1
	v_add_f32_dpp v47, v47, v47 quad_perm:[1,0,3,2] row_mask:0xf bank_mask:0xf
	s_nop 1
	v_add_f32_dpp v47, v47, v47 quad_perm:[2,3,0,1] row_mask:0xf bank_mask:0xf
	s_nop 1
	v_add_f32_dpp v47, v47, v47 row_half_mirror row_mask:0xf bank_mask:0xf
	s_nop 1
	v_add_f32_dpp v47, v47, v47 row_mirror row_mask:0xf bank_mask:0xf
	v_mov_b32_e32 v49, v47
	v_mov_b32_e32 v53, v47
	s_nop 1
	v_permlane16_swap_b32_e32 v49, v53
	s_nop 1
	v_add_f32_e32 v47, v49, v53
	v_mov_b32_e32 v49, v47
	v_mov_b32_e32 v53, v47
	s_nop 1
	v_permlane32_swap_b32_e32 v49, v53
	s_nop 1
	v_add_f32_e32 v47, v49, v53
	v_xor_b32_e32 v49, 2, v239
	v_cmp_lt_i32_e32 vcc, v49, v51
	s_nop 1
	v_cndmask_b32_e32 v49, v239, v49, vcc
	v_lshlrev_b32_e32 v49, 2, v49
	v_xor_b32_e32 v53, 4, v239
	v_cmp_lt_i32_e32 vcc, v53, v51
	s_nop 1
	v_cndmask_b32_e32 v53, v239, v53, vcc
	v_lshlrev_b32_e32 v53, 2, v53
	v_xor_b32_e32 v66, 8, v239
	v_cmp_lt_i32_e32 vcc, v66, v51
	s_nop 1
	v_cndmask_b32_e32 v66, v239, v66, vcc
	v_lshlrev_b32_e32 v70, 2, v66
	v_xor_b32_e32 v66, 16, v239
	v_cmp_lt_i32_e32 vcc, v66, v51
	s_nop 1
	v_cndmask_b32_e32 v66, v239, v66, vcc
	v_lshlrev_b32_e32 v71, 2, v66
	v_xor_b32_e32 v66, 32, v239
	v_cmp_lt_i32_e32 vcc, v66, v51
	s_nop 1
	v_cndmask_b32_e32 v51, v239, v66, vcc
	v_lshlrev_b32_e32 v72, 2, v51
	v_fmac_f32_e32 v64, 0xba800000, v47
	v_fmac_f32_e32 v65, 0xba800000, v47
	v_fmac_f32_e32 v59, 0xba800000, v47
	v_fmac_f32_e32 v58, 0xba800000, v47
	v_mov_b32_e32 v66, v59
	v_mov_b32_e32 v67, v65
	v_mov_b32_e32 v59, v64
	v_pk_mul_f32 v[68:69], v[66:67], v[66:67]
	v_pk_mul_f32 v[64:65], v[58:59], v[58:59]
	v_fmac_f32_e32 v62, 0xba800000, v47
	v_pk_mov_b32 v[74:75], v[64:65], v[68:69] op_sel:[1,0]
	v_mov_b32_e32 v65, v69
	v_pk_add_f32 v[64:65], v[74:75], v[64:65]
	v_fmac_f32_e32 v63, 0xba800000, v47
	v_fmac_f32_e32 v61, 0xba800000, v47
	v_pk_add_f32 v[68:69], v[64:65], v[64:65] op_sel_hi:[0,1]
	v_fmac_f32_e32 v60, 0xba800000, v47
	v_mov_b32_e32 v64, v61
	v_mov_b32_e32 v65, v63
	v_mov_b32_e32 v61, v62
	v_pk_mul_f32 v[74:75], v[64:65], v[64:65]
	v_pk_mul_f32 v[62:63], v[60:61], v[60:61]
	v_fmac_f32_e32 v54, 0xba800000, v47
	v_pk_mov_b32 v[76:77], v[62:63], v[74:75] op_sel:[1,0]
	v_mov_b32_e32 v63, v75
	v_pk_add_f32 v[62:63], v[76:77], v[62:63]
	v_fmac_f32_e32 v55, 0xba800000, v47
	v_pk_add_f32 v[62:63], v[62:63], v[62:63] op_sel_hi:[0,1]
	v_fmac_f32_e32 v56, 0xba800000, v47
	v_mul_f32_e32 v62, v54, v54
	v_fmac_f32_e32 v57, 0xba800000, v47
	v_pk_fma_f32 v[74:75], v[54:55], v[54:55], v[62:63] op_sel_hi:[1,1,0]
	v_mul_f32_e32 v62, v56, v56
	v_pk_fma_f32 v[76:77], v[56:57], v[56:57], v[62:63] op_sel_hi:[1,1,0]
	v_fmac_f32_e32 v48, 0xba800000, v47
	v_fmac_f32_e32 v46, 0xba800000, v47
	v_fmac_f32_e32 v52, 0xba800000, v47
	v_fmac_f32_e32 v50, 0xba800000, v47
	v_mul_f32_e32 v74, v50, v50
	v_mul_f32_e32 v76, v52, v52
	v_mul_f32_e32 v68, v46, v46
	v_mul_f32_e32 v62, v48, v48
	v_pk_add_f32 v[74:75], v[74:75], v[76:77]
	v_pk_add_f32 v[62:63], v[68:69], v[62:63]
	s_nop 0
	v_pk_add_f32 v[62:63], v[74:75], v[62:63]
	s_nop 0
	v_add_f32_e32 v47, v62, v63
	s_nop 1
	v_add_f32_dpp v47, v47, v47 quad_perm:[1,0,3,2] row_mask:0xf bank_mask:0xf
	s_nop 1
	v_add_f32_dpp v47, v47, v47 quad_perm:[2,3,0,1] row_mask:0xf bank_mask:0xf
	s_nop 1
	v_add_f32_dpp v47, v47, v47 row_half_mirror row_mask:0xf bank_mask:0xf
; #define GAS __attribute__((address_space(1)))
; __device__ __forceinline__ unsigned pk2(float lo, float hi) { return f2bf(lo) | (f2bf(hi) << 16); }
; #define WSB(F, off) ((bf16*)(wsq((F).ws) + (off)))
; __device__ __forceinline__ void ln_rows(const Frame& F, int idx, bool final_out, int row_lo, int row_hi, int gw0, int NGW, bool comb = false) {
;     ...
;         const float mean = wave_sum(s) * (1.f / D); float s2 = 0.f;
; #pragma unroll
;         for (int j = 0; j < 4; ++j) { v[j] = v[j] - mean; s2 += (v[j].x * v[j].x + v[j].y * v[j].y) + (v[j].z * v[j].z + v[j].w * v[j].w); }
;         const float rstd = 1.f / sqrtf(wave_sum(s2) * (1.f / D) + LN_EPS);
; #pragma unroll
;         for (int j = 0; j < 4; ++j) v[j] = v[j] * rstd * gv[j] + bv[j];
;         if (!final_out) { GAS v4u* o = (GAS v4u*)(WSB(F, WS_HB) + (size_t)m * D) + tc.lane;
; #pragma unroll
;             for (int j = 0; j < 2; ++j) o[64 * j] = (v4u){pk2(v[2 * j].x, v[2 * j].y), pk2(v[2 * j].z, v[2 * j].w), pk2(v[2 * j + 1].x, v[2 * j + 1].y), pk2(v[2 * j + 1].z, v[2 * j + 1].w)}; }
	s_nop 1
	v_add_f32_dpp v47, v47, v47 row_mirror row_mask:0xf bank_mask:0xf
	v_mov_b32_e32 v51, v47
	v_mov_b32_e32 v72, v47
	s_nop 1
	v_permlane16_swap_b32_e32 v51, v72
	s_nop 1
	v_add_f32_e32 v47, v51, v72
	v_mov_b32_e32 v51, v47
	v_mov_b32_e32 v72, v47
	s_nop 1
	v_permlane32_swap_b32_e32 v51, v72
	s_nop 1
	v_add_f32_e32 v47, v51, v72
	v_fmamk_f32 v47, v47, 0x3a800000, v235
	v_cmp_gt_f32_e32 vcc, s89, v47
	v_mul_f32_e32 v51, 0x4f800000, v47
	s_nop 0
	v_cndmask_b32_e32 v47, v47, v51, vcc
	v_sqrt_f32_e32 v51, v47
	s_nop 0
	v_add_u32_e32 v62, -1, v51
	v_fma_f32 v63, -v62, v51, v47
	v_cmp_ge_f32_e64 s[8:9], 0, v63
	v_add_u32_e32 v63, 1, v51
	s_nop 0
	v_cndmask_b32_e64 v62, v51, v62, s[8:9]
	v_fma_f32 v51, -v63, v51, v47
	v_cmp_lt_f32_e64 s[8:9], 0, v51
	s_nop 1
	v_cndmask_b32_e64 v51, v62, v63, s[8:9]
	v_mul_f32_e32 v62, 0x37800000, v51
	v_cndmask_b32_e32 v51, v51, v62, vcc
	v_cmp_class_f32_e32 vcc, v47, v236
	s_nop 1
	v_cndmask_b32_e32 v47, v51, v47, vcc
	v_div_scale_f32 v51, s[8:9], v47, v47, 1.0
	v_rcp_f32_e32 v62, v51
	s_nop 0
	v_fma_f32 v63, -v51, v62, 1.0
	v_fmac_f32_e32 v62, v63, v62
	v_div_scale_f32 v63, vcc, 1.0, v47, 1.0
	v_mul_f32_e32 v68, v63, v62
	v_fma_f32 v69, -v51, v68, v63
	v_fmac_f32_e32 v68, v69, v62
	v_fma_f32 v51, -v51, v68, v63
	v_div_fmas_f32 v51, v51, v62, v68
	v_div_fixup_f32 v68, v51, v47, 1.0
	v_pk_mul_f32 v[58:59], v[58:59], v[68:69] op_sel_hi:[1,0]
	v_mov_b32_e32 v47, v48
	v_pk_mul_f32 v[62:63], v[66:67], v[68:69] op_sel_hi:[1,0]
	v_pk_mul_f32 v[60:61], v[60:61], v[68:69] op_sel_hi:[1,0]
	v_pk_mul_f32 v[46:47], v[46:47], v[68:69] op_sel_hi:[1,0]
	v_pk_fma_f32 v[58:59], v[6:7], v[58:59], v[14:15]
	v_pk_fma_f32 v[66:67], v[20:21], v[46:47], v[28:29]
	v_pk_fma_f32 v[46:47], v[2:3], v[60:61], v[10:11]
	v_pk_fma_f32 v[60:61], v[8:9], v[62:63], v[16:17]
	v_lshl_add_u64 v[62:63], s[16:17], 0, v[44:45]
	v_bfe_u32 v44, v58, 16, 1
	v_add3_u32 v44, v58, v44, s72
	v_bfe_u32 v45, v59, 16, 1
	v_lshrrev_b32_e32 v44, 16, v44
	v_add3_u32 v45, v59, v45, s72
	v_and_or_b32 v44, v45, s88, v44
	v_bfe_u32 v45, v60, 16, 1
	v_add3_u32 v45, v60, v45, s72
	v_bfe_u32 v48, v61, 16, 1
	v_lshrrev_b32_e32 v45, 16, v45
	v_add3_u32 v48, v61, v48, s72
	v_and_or_b32 v45, v48, s88, v45
	v_bfe_u32 v48, v46, 16, 1
	v_pk_mul_f32 v[64:65], v[64:65], v[68:69] op_sel_hi:[1,0]
	v_add3_u32 v46, v46, v48, s72
	v_bfe_u32 v48, v47, 16, 1
	v_pk_fma_f32 v[64:65], v[4:5], v[64:65], v[12:13]
	v_lshrrev_b32_e32 v46, 16, v46
	v_add3_u32 v47, v47, v48, s72
	v_and_or_b32 v46, v47, s88, v46
	v_bfe_u32 v47, v64, 16, 1
	v_add3_u32 v47, v64, v47, s72
	v_bfe_u32 v48, v65, 16, 1
	v_pk_mul_f32 v[54:55], v[54:55], v[68:69] op_sel_hi:[1,0]
	v_lshrrev_b32_e32 v47, 16, v47
	v_add3_u32 v48, v65, v48, s72
	v_pk_fma_f32 v[54:55], v[22:23], v[54:55], v[30:31]
	v_and_or_b32 v47, v48, s88, v47
	global_store_dwordx4 v[62:63], v[44:47], off
	v_pk_mul_f32 v[56:57], v[56:57], v[68:69] op_sel_hi:[1,0]
	v_mov_b32_e32 v51, v52
	v_bfe_u32 v44, v54, 16, 1
	v_add3_u32 v44, v54, v44, s72
	v_bfe_u32 v45, v55, 16, 1
	v_pk_fma_f32 v[56:57], v[24:25], v[56:57], v[32:33]
	v_lshrrev_b32_e32 v44, 16, v44
	v_add3_u32 v45, v55, v45, s72
	v_and_or_b32 v44, v45, s88, v44
	v_bfe_u32 v45, v56, 16, 1
	v_pk_mul_f32 v[50:51], v[50:51], v[68:69] op_sel_hi:[1,0]
	v_add3_u32 v45, v56, v45, s72
	v_bfe_u32 v46, v57, 16, 1
	v_pk_fma_f32 v[50:51], v[18:19], v[50:51], v[26:27]
	v_lshrrev_b32_e32 v45, 16, v45
	v_add3_u32 v46, v57, v46, s72
	v_and_or_b32 v45, v46, s88, v45
	v_bfe_u32 v46, v50, 16, 1
	v_add3_u32 v46, v50, v46, s72
	v_bfe_u32 v47, v51, 16, 1
	v_lshrrev_b32_e32 v46, 16, v46
	v_add3_u32 v47, v51, v47, s72
	v_and_or_b32 v46, v47, s88, v46
	v_bfe_u32 v47, v66, 16, 1
	v_add3_u32 v47, v66, v47, s72
	v_bfe_u32 v48, v67, 16, 1
	v_lshrrev_b32_e32 v47, 16, v47
	v_add3_u32 v48, v67, v48, s72
	v_and_or_b32 v47, v48, s88, v47
	global_store_dwordx4 v[62:63], v[44:47], off offset:1024
	s_cbranch_scc1 .LBB0_1466
	s_waitcnt vmcnt(3)
	v_lshlrev_b32_e32 v57, 16, v35
	v_lshlrev_b32_e32 v56, 16, v34
	v_and_b32_e32 v35, 0xffff0000, v35
	v_and_b32_e32 v34, 0xffff0000, v34
	v_pk_add_f32 v[58:59], v[56:57], v[34:35]
	s_waitcnt vmcnt(2)
	v_lshlrev_b32_e32 v50, 16, v41
	v_and_b32_e32 v54, 0xffff0000, v41
	v_add_f32_e32 v41, v58, v59
	v_lshlrev_b32_e32 v59, 16, v37
	v_lshlrev_b32_e32 v58, 16, v36
	v_and_b32_e32 v37, 0xffff0000, v37
	v_and_b32_e32 v36, 0xffff0000, v36
	v_pk_add_f32 v[60:61], v[58:59], v[36:37]
	v_lshlrev_b32_e32 v44, 16, v38
	v_and_b32_e32 v45, 0xffff0000, v38
	v_lshlrev_b32_e32 v38, 16, v39
	v_and_b32_e32 v39, 0xffff0000, v39
	v_pk_add_f32 v[60:61], v[60:61], v[60:61] op_sel_hi:[0,1]
	v_lshlrev_b32_e32 v46, 16, v40
	v_and_b32_e32 v40, 0xffff0000, v40
	v_add_f32_e32 v55, 0, v41
	v_add_f32_e32 v47, v44, v45
	v_add_f32_e32 v41, v38, v39
	v_mov_b32_e32 v51, v61
	v_pk_add_f32 v[62:63], v[46:47], v[40:41]
	v_pk_add_f32 v[60:61], v[50:51], v[54:55]
	s_ashr_i32 s13, s12, 31
	v_pk_add_f32 v[60:61], v[62:63], v[60:61]
	s_lshl_b64 s[12:13], s[12:13], 11
	v_add_f32_e32 v41, v60, v61
	s_nop 1
	v_add_f32_dpp v41, v41, v41 quad_perm:[1,0,3,2] row_mask:0xf bank_mask:0xf
	s_nop 1
	v_add_f32_dpp v41, v41, v41 quad_perm:[2,3,0,1] row_mask:0xf bank_mask:0xf
	s_nop 1
	v_add_f32_dpp v41, v41, v41 row_half_mirror row_mask:0xf bank_mask:0xf
	s_nop 1
	v_add_f32_dpp v41, v41, v41 row_mirror row_mask:0xf bank_mask:0xf
	v_mov_b32_e32 v47, v41
	v_mov_b32_e32 v72, v41
	s_nop 1
	v_permlane16_swap_b32_e32 v47, v72
	s_nop 1
	v_add_f32_e32 v41, v47, v72
	v_mov_b32_e32 v47, v41
	v_mov_b32_e32 v72, v41
	s_nop 1
	v_permlane32_swap_b32_e32 v47, v72
	s_nop 1
	v_add_f32_e32 v41, v47, v72
	v_fmac_f32_e32 v34, 0xba800000, v41
	v_fmac_f32_e32 v35, 0xba800000, v41
; #define GAS __attribute__((address_space(1)))
; __device__ __forceinline__ unsigned pk2(float lo, float hi) { return f2bf(lo) | (f2bf(hi) << 16); }
; #define WSB(F, off) ((bf16*)(wsq((F).ws) + (off)))
; __device__ __forceinline__ void ln_rows(const Frame& F, int idx, bool final_out, int row_lo, int row_hi, int gw0, int NGW, bool comb = false) {
;     ...
;         const float mean = wave_sum(s) * (1.f / D); float s2 = 0.f;
; #pragma unroll
;         for (int j = 0; j < 4; ++j) { v[j] = v[j] - mean; s2 += (v[j].x * v[j].x + v[j].y * v[j].y) + (v[j].z * v[j].z + v[j].w * v[j].w); }
;         const float rstd = 1.f / sqrtf(wave_sum(s2) * (1.f / D) + LN_EPS);
; #pragma unroll
;         for (int j = 0; j < 4; ++j) v[j] = v[j] * rstd * gv[j] + bv[j];
;         if (!final_out) { GAS v4u* o = (GAS v4u*)(WSB(F, WS_HB) + (size_t)m * D) + tc.lane;
; #pragma unroll
;             for (int j = 0; j < 2; ++j) o[64 * j] = (v4u){pk2(v[2 * j].x, v[2 * j].y), pk2(v[2 * j].z, v[2 * j].w), pk2(v[2 * j + 1].x, v[2 * j + 1].y), pk2(v[2 * j + 1].z, v[2 * j + 1].w)}; }
	v_fmac_f32_e32 v57, 0xba800000, v41
	v_fmac_f32_e32 v56, 0xba800000, v41
	v_mov_b32_e32 v60, v57
	v_mov_b32_e32 v61, v35
	v_mov_b32_e32 v57, v34
	v_pk_mul_f32 v[62:63], v[60:61], v[60:61]
	v_pk_mul_f32 v[34:35], v[56:57], v[56:57]
	v_fmac_f32_e32 v36, 0xba800000, v41
	v_pk_mov_b32 v[64:65], v[34:35], v[62:63] op_sel:[1,0]
	v_mov_b32_e32 v35, v63
	v_fmac_f32_e32 v37, 0xba800000, v41
	v_fmac_f32_e32 v59, 0xba800000, v41
	v_pk_add_f32 v[34:35], v[64:65], v[34:35]
	v_fmac_f32_e32 v58, 0xba800000, v41
	v_mov_b32_e32 v62, v59
	v_mov_b32_e32 v63, v37
	v_mov_b32_e32 v59, v36
	v_pk_add_f32 v[34:35], v[34:35], v[34:35] op_sel_hi:[0,1]
	v_pk_mul_f32 v[64:65], v[62:63], v[62:63]
	v_pk_mul_f32 v[36:37], v[58:59], v[58:59]
	v_fmac_f32_e32 v44, 0xba800000, v41
	v_pk_mov_b32 v[66:67], v[36:37], v[64:65] op_sel:[1,0]
	v_mov_b32_e32 v37, v65
	v_fmac_f32_e32 v45, 0xba800000, v41
	v_fmac_f32_e32 v38, 0xba800000, v41
	v_mul_f32_e32 v34, v44, v44
	v_pk_add_f32 v[36:37], v[66:67], v[36:37]
	v_fmac_f32_e32 v39, 0xba800000, v41
	v_pk_fma_f32 v[64:65], v[44:45], v[44:45], v[34:35] op_sel_hi:[1,1,0]
	v_mul_f32_e32 v34, v38, v38
	v_pk_add_f32 v[36:37], v[36:37], v[36:37] op_sel_hi:[0,1]
	v_pk_fma_f32 v[66:67], v[38:39], v[38:39], v[34:35] op_sel_hi:[1,1,0]
	v_fmac_f32_e32 v54, 0xba800000, v41
	v_fmac_f32_e32 v50, 0xba800000, v41
	v_fmac_f32_e32 v40, 0xba800000, v41
	v_fmac_f32_e32 v46, 0xba800000, v41
	v_mul_f32_e32 v64, v46, v46
	v_mul_f32_e32 v66, v40, v40
	v_mul_f32_e32 v34, v50, v50
	v_mul_f32_e32 v36, v54, v54
	v_pk_add_f32 v[64:65], v[64:65], v[66:67]
	v_pk_add_f32 v[34:35], v[34:35], v[36:37]
	v_mov_b32_e32 v47, v40
	v_pk_add_f32 v[34:35], v[64:65], v[34:35]
	v_mov_b32_e32 v51, v54
	v_add_f32_e32 v34, v34, v35
	s_nop 1
	v_add_f32_dpp v34, v34, v34 quad_perm:[1,0,3,2] row_mask:0xf bank_mask:0xf
	s_nop 1
	v_add_f32_dpp v34, v34, v34 quad_perm:[2,3,0,1] row_mask:0xf bank_mask:0xf
	s_nop 1
	v_add_f32_dpp v34, v34, v34 row_half_mirror row_mask:0xf bank_mask:0xf
	s_nop 1
	v_add_f32_dpp v34, v34, v34 row_mirror row_mask:0xf bank_mask:0xf
	v_mov_b32_e32 v72, v34
	v_mov_b32_e32 v71, v34
	s_nop 1
	v_permlane16_swap_b32_e32 v72, v71
	s_nop 1
	v_add_f32_e32 v34, v72, v71
	v_mov_b32_e32 v72, v34
	v_mov_b32_e32 v71, v34
	s_nop 1
	v_permlane32_swap_b32_e32 v72, v71
	s_nop 1
	v_add_f32_e32 v1, v72, v71
	v_fmamk_f32 v1, v1, 0x3a800000, v235
	v_mul_f32_e32 v34, 0x4f800000, v1
	v_cmp_gt_f32_e32 vcc, s89, v1
	s_nop 1
	v_cndmask_b32_e32 v1, v1, v34, vcc
	v_sqrt_f32_e32 v34, v1
	s_nop 0
	v_add_u32_e32 v35, -1, v34
	v_fma_f32 v36, -v35, v34, v1
	v_cmp_ge_f32_e64 s[8:9], 0, v36
	v_add_u32_e32 v36, 1, v34
	s_nop 0
	v_cndmask_b32_e64 v35, v34, v35, s[8:9]
	v_fma_f32 v34, -v36, v34, v1
	v_cmp_lt_f32_e64 s[8:9], 0, v34
	s_nop 1
	v_cndmask_b32_e64 v34, v35, v36, s[8:9]
	v_mul_f32_e32 v35, 0x37800000, v34
	v_cndmask_b32_e32 v34, v34, v35, vcc
	v_cmp_class_f32_e32 vcc, v1, v236
	s_nop 1
	v_cndmask_b32_e32 v1, v34, v1, vcc
	v_div_scale_f32 v34, s[8:9], v1, v1, 1.0
	v_rcp_f32_e32 v35, v34
	s_mov_b64 s[8:9], s[46:47]
	s_add_u32 s8, s8, s12
	v_fma_f32 v36, -v34, v35, 1.0
	v_fmac_f32_e32 v35, v36, v35
	v_div_scale_f32 v36, vcc, 1.0, v1, 1.0
	v_mul_f32_e32 v37, v36, v35
	v_fma_f32 v41, -v34, v37, v36
	v_fmac_f32_e32 v37, v41, v35
	v_fma_f32 v34, -v34, v37, v36
	v_div_fmas_f32 v34, v34, v35, v37
	v_div_fixup_f32 v34, v34, v1, 1.0
	v_pk_mul_f32 v[36:37], v[56:57], v[34:35] op_sel_hi:[1,0]
	v_pk_mul_f32 v[48:49], v[60:61], v[34:35] op_sel_hi:[1,0]
	v_pk_mul_f32 v[52:53], v[58:59], v[34:35] op_sel_hi:[1,0]
	v_pk_mul_f32 v[56:57], v[62:63], v[34:35] op_sel_hi:[1,0]
	v_pk_mul_f32 v[44:45], v[44:45], v[34:35] op_sel_hi:[1,0]
	v_pk_mul_f32 v[38:39], v[38:39], v[34:35] op_sel_hi:[1,0]
	v_pk_mul_f32 v[40:41], v[46:47], v[34:35] op_sel_hi:[1,0]
	v_pk_mul_f32 v[34:35], v[50:51], v[34:35] op_sel_hi:[1,0]
	v_pk_fma_f32 v[48:49], v[8:9], v[48:49], v[16:17]
	v_pk_fma_f32 v[46:47], v[20:21], v[34:35], v[28:29]
	v_pk_fma_f32 v[34:35], v[6:7], v[36:37], v[14:15]
	v_pk_fma_f32 v[52:53], v[2:3], v[52:53], v[10:11]
	v_bfe_u32 v1, v34, 16, 1
	v_add3_u32 v1, v34, v1, s72
	v_bfe_u32 v34, v35, 16, 1
	v_lshrrev_b32_e32 v1, 16, v1
	v_add3_u32 v34, v35, v34, s72
	v_and_or_b32 v34, v34, s88, v1
	v_bfe_u32 v1, v48, 16, 1
	v_add3_u32 v1, v48, v1, s72
	v_bfe_u32 v35, v49, 16, 1
	v_lshrrev_b32_e32 v1, 16, v1
	v_add3_u32 v35, v49, v35, s72
	v_and_or_b32 v35, v35, s88, v1
	v_bfe_u32 v1, v52, 16, 1
	v_add3_u32 v1, v52, v1, s72
	v_bfe_u32 v36, v53, 16, 1
	v_pk_fma_f32 v[50:51], v[4:5], v[56:57], v[12:13]
	s_addc_u32 s9, s9, s13
	v_lshrrev_b32_e32 v1, 16, v1
	v_add3_u32 v36, v53, v36, s72
	v_lshl_add_u64 v[54:55], v[42:43], 4, s[8:9]
	s_mov_b64 s[8:9], 0x8200000
	v_and_or_b32 v36, v36, s88, v1
	v_bfe_u32 v1, v50, 16, 1
	v_lshl_add_u64 v[56:57], v[54:55], 0, s[8:9]
	v_add3_u32 v1, v50, v1, s72
	v_bfe_u32 v37, v51, 16, 1
	s_mov_b32 s8, 0x8200000
	v_pk_fma_f32 v[44:45], v[22:23], v[44:45], v[30:31]
	v_lshrrev_b32_e32 v1, 16, v1
	v_add3_u32 v37, v51, v37, s72
	v_add_co_u32_e32 v48, vcc, s8, v54
	v_and_or_b32 v37, v37, s88, v1
	s_nop 0
	v_addc_co_u32_e32 v49, vcc, 0, v55, vcc
	v_bfe_u32 v1, v44, 16, 1
	global_store_dwordx4 v[48:49], v[34:37], off
	v_add3_u32 v1, v44, v1, s72
	v_pk_fma_f32 v[38:39], v[24:25], v[38:39], v[32:33]
	v_bfe_u32 v34, v45, 16, 1
	v_lshrrev_b32_e32 v1, 16, v1
	v_add3_u32 v34, v45, v34, s72
	v_and_or_b32 v34, v34, s88, v1
	v_bfe_u32 v1, v38, 16, 1
	v_add3_u32 v1, v38, v1, s72
	v_bfe_u32 v35, v39, 16, 1
	v_pk_fma_f32 v[40:41], v[18:19], v[40:41], v[26:27]
	v_lshrrev_b32_e32 v1, 16, v1
	v_add3_u32 v35, v39, v35, s72
	v_and_or_b32 v35, v35, s88, v1
	v_bfe_u32 v1, v40, 16, 1
	v_add3_u32 v1, v40, v1, s72
	v_bfe_u32 v36, v41, 16, 1
	v_lshrrev_b32_e32 v1, 16, v1
	v_add3_u32 v36, v41, v36, s72
	v_and_or_b32 v36, v36, s88, v1
	v_bfe_u32 v1, v46, 16, 1
	v_add3_u32 v1, v46, v1, s72
	v_bfe_u32 v37, v47, 16, 1
	v_lshrrev_b32_e32 v1, 16, v1
	v_add3_u32 v37, v47, v37, s72
	v_and_or_b32 v37, v37, s88, v1
	global_store_dwordx4 v[56:57], v[34:37], off offset:1024
	s_branch .LBB0_1466

; #define GAS __attribute__((address_space(1)))
; #define WSB(F, off) ((bf16*)(wsq((F).ws) + (off)))
; __device__ __forceinline__ void ln_rows(const Frame& F, int idx, bool final_out, int row_lo, int row_hi, int gw0, int NGW, bool comb = false) {
;     ...
;     for (int m0 = row_lo + gw; m0 < row_hi; m0 += 2 * NGW) {
;         v4u w[2][2]; const bool two = m0 + NGW < row_hi;
; #pragma unroll
;         for (int r = 0; r < 2; ++r) { const int m = (r == 0 || two) ? m0 + r * NGW : m0; const GAS v4u* yr = (const GAS v4u*)(WSB(F, comb ? WS_HB : WS_YB) + (size_t)m * D) + tc.lane; w[r][0] = yr[0]; w[r][1] = yr[64]; }
; #pragma unroll
;         for (int r = 0; r < 2; ++r) { const int m = m0 + r * NGW; if (r == 1 && !two) break;
;         f32x4 v[4]; float s = 0.f;
; #pragma unroll
;         for (int j = 0; j < 2; ++j) { const v4u x = w[r][j]; v[2 * j] = (f32x4){bflo(x.x), bfhi(x.x), bflo(x.y), bfhi(x.y)}; v[2 * j + 1] = (f32x4){bflo(x.z), bfhi(x.z), bflo(x.w), bfhi(x.w)}; }
;         if (comb) {
;             const GAS f32x4* pa = (const GAS f32x4*)((const float*)WSB(F, WS_ACT) + (size_t)(m - MP) * D) + 2 * tc.lane; const GAS f32x4* pb = pa + (size_t)512 * D / 4;
; #pragma unroll
;             for (int j = 0; j < 2; ++j) { v[2 * j] = v[2 * j] * ALPHA + (pa[128 * j] + pb[128 * j]) * 0.5f; v[2 * j + 1] = v[2 * j + 1] * ALPHA + (pa[128 * j + 1] + pb[128 * j + 1]) * 0.5f; } }
; #pragma unroll
;         for (int j = 0; j < 4; ++j) s += (v[j].x + v[j].y) + (v[j].z + v[j].w);
;         const float mean = wave_sum(s) * (1.f / D); float s2 = 0.f;
; #pragma unroll
;         for (int j = 0; j < 4; ++j) { v[j] = v[j] - mean; s2 += (v[j].x * v[j].x + v[j].y * v[j].y) + (v[j].z * v[j].z + v[j].w * v[j].w); }
;         const float rstd = 1.f / sqrtf(wave_sum(s2) * (1.f / D) + LN_EPS);
.LBB0_1882:
	v_readlane_b32 s4, v253, 7
	s_add_i32 s4, s4, s10
	s_mov_b64 s[6:7], s[46:47]
	s_addk_i32 s4, 0xfea0
	s_add_u32 s6, s6, s2
	s_addc_u32 s7, s7, s3
	v_lshlrev_b64 v[44:45], 4, v[42:43]
	v_lshl_add_u64 v[34:35], s[6:7], 0, v[44:45]
	s_mov_b32 s6, 0xf7f00000
	s_mov_b32 s7, -1
	s_mov_b32 s5, 0xf7f00000
	v_lshl_add_u64 v[36:37], v[34:35], 0, s[6:7]
	v_add_co_u32_e32 v34, vcc, s5, v34
	s_cmp_lt_i32 s4, 0x10000
	s_nop 0
	v_addc_co_u32_e32 v35, vcc, -1, v35, vcc
	global_load_dwordx4 v[60:63], v[34:35], off
	global_load_dwordx4 v[46:49], v[36:37], off offset:1024
	v_readlane_b32 s5, v253, 62
	s_cselect_b32 s5, s5, 0
	s_add_i32 s6, s5, s10
	s_ashr_i32 s7, s6, 31
	s_mov_b64 s[8:9], s[46:47]
	s_lshl_b64 s[6:7], s[6:7], 11
	s_add_u32 s6, s8, s6
	s_addc_u32 s7, s9, s7
	v_lshl_add_u64 v[34:35], s[6:7], 0, v[44:45]
	s_mov_b64 s[6:7], 0x100000
	s_mov_b32 s5, 0x100000
	v_lshl_add_u64 v[38:39], v[34:35], 0, s[6:7]
	v_add_co_u32_e32 v34, vcc, s5, v34
	s_mov_b64 s[6:7], s[46:47]
	s_nop 0
	v_addc_co_u32_e32 v35, vcc, 0, v35, vcc
	global_load_dwordx4 v[34:37], v[34:35], off
	s_nop 0
	global_load_dwordx4 v[38:41], v[38:39], off offset:1024
	s_add_u32 s8, s6, s2
	s_addc_u32 s9, s7, s3
	s_cmp_gt_i32 s4, 0xffff
	s_waitcnt vmcnt(0)
	v_lshlrev_b32_e32 v59, 16, v61
	v_lshlrev_b32_e32 v58, 16, v60
	v_and_b32_e32 v65, 0xffff0000, v61
	v_and_b32_e32 v64, 0xffff0000, v60
	v_pk_add_f32 v[60:61], v[58:59], v[64:65]
	v_lshlrev_b32_e32 v54, 16, v46
	v_add_f32_e32 v1, v60, v61
	v_lshlrev_b32_e32 v61, 16, v63
	v_lshlrev_b32_e32 v60, 16, v62
	v_and_b32_e32 v63, 0xffff0000, v63
	v_and_b32_e32 v62, 0xffff0000, v62
	v_and_b32_e32 v55, 0xffff0000, v46
	v_lshlrev_b32_e32 v56, 16, v47
	v_and_b32_e32 v57, 0xffff0000, v47
	v_pk_add_f32 v[66:67], v[60:61], v[62:63]
	v_lshlrev_b32_e32 v50, 16, v48
	v_and_b32_e32 v52, 0xffff0000, v48
	v_lshlrev_b32_e32 v46, 16, v49
	v_and_b32_e32 v48, 0xffff0000, v49
	v_add_f32_e32 v49, 0, v1
	v_pk_add_f32 v[66:67], v[66:67], v[66:67] op_sel_hi:[0,1]
	v_add_f32_e32 v51, v54, v55
	v_add_f32_e32 v53, v56, v57
	v_and_b32_e32 v1, 64, v239
	v_pk_add_f32 v[68:69], v[50:51], v[52:53]
	v_mov_b32_e32 v47, v67
	v_add_u32_e32 v51, 64, v1
	v_xor_b32_e32 v1, 1, v239
	v_pk_add_f32 v[66:67], v[46:47], v[48:49]
	v_cmp_lt_i32_e32 vcc, v1, v51
	v_pk_add_f32 v[66:67], v[68:69], v[66:67]
	s_nop 0
	v_cndmask_b32_e32 v1, v239, v1, vcc
	v_add_f32_e32 v47, v66, v67
	v_lshlrev_b32_e32 v1, 2, v1
	s_nop 1
	v_add_f32_dpp v47, v47, v47 quad_perm:[1,0,3,2] row_mask:0xf bank_mask:0xf
	s_nop 1
	v_add_f32_dpp v47, v47, v47 quad_perm:[2,3,0,1] row_mask:0xf bank_mask:0xf
	s_nop 1
	v_add_f32_dpp v47, v47, v47 row_half_mirror row_mask:0xf bank_mask:0xf
	s_nop 1
	v_add_f32_dpp v47, v47, v47 row_mirror row_mask:0xf bank_mask:0xf
	v_mov_b32_e32 v49, v47
	v_mov_b32_e32 v53, v47
	s_nop 1
	v_permlane16_swap_b32_e32 v49, v53
	s_nop 1
	v_add_f32_e32 v47, v49, v53
	v_mov_b32_e32 v49, v47
	v_mov_b32_e32 v53, v47
	s_nop 1
	v_permlane32_swap_b32_e32 v49, v53
	s_nop 1
	v_add_f32_e32 v47, v49, v53
	v_xor_b32_e32 v49, 2, v239
	v_cmp_lt_i32_e32 vcc, v49, v51
	s_nop 1
	v_cndmask_b32_e32 v49, v239, v49, vcc
	v_lshlrev_b32_e32 v49, 2, v49
	v_xor_b32_e32 v53, 4, v239
	v_cmp_lt_i32_e32 vcc, v53, v51
	s_nop 1
	v_cndmask_b32_e32 v53, v239, v53, vcc
	v_lshlrev_b32_e32 v53, 2, v53
	v_xor_b32_e32 v66, 8, v239
	v_cmp_lt_i32_e32 vcc, v66, v51
	s_nop 1
	v_cndmask_b32_e32 v66, v239, v66, vcc
	v_lshlrev_b32_e32 v70, 2, v66
	v_xor_b32_e32 v66, 16, v239
	v_cmp_lt_i32_e32 vcc, v66, v51
	s_nop 1
	v_cndmask_b32_e32 v66, v239, v66, vcc
	v_lshlrev_b32_e32 v71, 2, v66
	v_xor_b32_e32 v66, 32, v239
	v_cmp_lt_i32_e32 vcc, v66, v51
	s_nop 1
	v_cndmask_b32_e32 v51, v239, v66, vcc
	v_lshlrev_b32_e32 v72, 2, v51
	v_fmac_f32_e32 v64, 0xba800000, v47
	v_fmac_f32_e32 v65, 0xba800000, v47
	v_fmac_f32_e32 v59, 0xba800000, v47
	v_fmac_f32_e32 v58, 0xba800000, v47
	v_mov_b32_e32 v66, v59
	v_mov_b32_e32 v67, v65
	v_mov_b32_e32 v59, v64
	v_pk_mul_f32 v[68:69], v[66:67], v[66:67]
	v_pk_mul_f32 v[64:65], v[58:59], v[58:59]
	v_fmac_f32_e32 v62, 0xba800000, v47
	v_pk_mov_b32 v[74:75], v[64:65], v[68:69] op_sel:[1,0]
	v_mov_b32_e32 v65, v69
	v_pk_add_f32 v[64:65], v[74:75], v[64:65]
	v_fmac_f32_e32 v63, 0xba800000, v47
	v_fmac_f32_e32 v61, 0xba800000, v47
	v_pk_add_f32 v[68:69], v[64:65], v[64:65] op_sel_hi:[0,1]
	v_fmac_f32_e32 v60, 0xba800000, v47
	v_mov_b32_e32 v64, v61
	v_mov_b32_e32 v65, v63
	v_mov_b32_e32 v61, v62
	v_pk_mul_f32 v[74:75], v[64:65], v[64:65]
	v_pk_mul_f32 v[62:63], v[60:61], v[60:61]
	v_fmac_f32_e32 v54, 0xba800000, v47
	v_pk_mov_b32 v[76:77], v[62:63], v[74:75] op_sel:[1,0]
	v_mov_b32_e32 v63, v75
	v_pk_add_f32 v[62:63], v[76:77], v[62:63]
	v_fmac_f32_e32 v55, 0xba800000, v47
	v_pk_add_f32 v[62:63], v[62:63], v[62:63] op_sel_hi:[0,1]
	v_fmac_f32_e32 v56, 0xba800000, v47
	v_mul_f32_e32 v62, v54, v54
	v_fmac_f32_e32 v57, 0xba800000, v47
	v_pk_fma_f32 v[74:75], v[54:55], v[54:55], v[62:63] op_sel_hi:[1,1,0]
	v_mul_f32_e32 v62, v56, v56
	v_pk_fma_f32 v[76:77], v[56:57], v[56:57], v[62:63] op_sel_hi:[1,1,0]
	v_fmac_f32_e32 v48, 0xba800000, v47
	v_fmac_f32_e32 v46, 0xba800000, v47
	v_fmac_f32_e32 v52, 0xba800000, v47
	v_fmac_f32_e32 v50, 0xba800000, v47
	v_mul_f32_e32 v74, v50, v50
	v_mul_f32_e32 v76, v52, v52
	v_mul_f32_e32 v68, v46, v46
	v_mul_f32_e32 v62, v48, v48
	v_pk_add_f32 v[74:75], v[74:75], v[76:77]
	v_pk_add_f32 v[62:63], v[68:69], v[62:63]
	s_nop 0
	v_pk_add_f32 v[62:63], v[74:75], v[62:63]
	s_nop 0
	v_add_f32_e32 v47, v62, v63
	s_nop 1
	v_add_f32_dpp v47, v47, v47 quad_perm:[1,0,3,2] row_mask:0xf bank_mask:0xf
	s_nop 1
	v_add_f32_dpp v47, v47, v47 quad_perm:[2,3,0,1] row_mask:0xf bank_mask:0xf
	s_nop 1
; #define GAS __attribute__((address_space(1)))
; __device__ __forceinline__ unsigned pk2(float lo, float hi) { return f2bf(lo) | (f2bf(hi) << 16); }
; #define WSB(F, off) ((bf16*)(wsq((F).ws) + (off)))
; __device__ __forceinline__ void ln_rows(const Frame& F, int idx, bool final_out, int row_lo, int row_hi, int gw0, int NGW, bool comb = false) {
;     ...
;         const float mean = wave_sum(s) * (1.f / D); float s2 = 0.f;
; #pragma unroll
;         for (int j = 0; j < 4; ++j) { v[j] = v[j] - mean; s2 += (v[j].x * v[j].x + v[j].y * v[j].y) + (v[j].z * v[j].z + v[j].w * v[j].w); }
;         const float rstd = 1.f / sqrtf(wave_sum(s2) * (1.f / D) + LN_EPS);
; #pragma unroll
;         for (int j = 0; j < 4; ++j) v[j] = v[j] * rstd * gv[j] + bv[j];
;         if (!final_out) { GAS v4u* o = (GAS v4u*)(WSB(F, WS_HB) + (size_t)m * D) + tc.lane;
; #pragma unroll
;             for (int j = 0; j < 2; ++j) o[64 * j] = (v4u){pk2(v[2 * j].x, v[2 * j].y), pk2(v[2 * j].z, v[2 * j].w), pk2(v[2 * j + 1].x, v[2 * j + 1].y), pk2(v[2 * j + 1].z, v[2 * j + 1].w)}; }
	v_add_f32_dpp v47, v47, v47 row_half_mirror row_mask:0xf bank_mask:0xf
	s_nop 1
	v_add_f32_dpp v47, v47, v47 row_mirror row_mask:0xf bank_mask:0xf
	v_mov_b32_e32 v51, v47
	v_mov_b32_e32 v72, v47
	s_nop 1
	v_permlane16_swap_b32_e32 v51, v72
	s_nop 1
	v_add_f32_e32 v47, v51, v72
	v_mov_b32_e32 v51, v47
	v_mov_b32_e32 v72, v47
	s_nop 1
	v_permlane32_swap_b32_e32 v51, v72
	s_nop 1
	v_add_f32_e32 v47, v51, v72
	v_fmamk_f32 v47, v47, 0x3a800000, v235
	v_cmp_gt_f32_e32 vcc, s89, v47
	v_mul_f32_e32 v51, 0x4f800000, v47
	s_nop 0
	v_cndmask_b32_e32 v47, v47, v51, vcc
	v_sqrt_f32_e32 v51, v47
	s_nop 0
	v_add_u32_e32 v62, -1, v51
	v_fma_f32 v63, -v62, v51, v47
	v_cmp_ge_f32_e64 s[6:7], 0, v63
	v_add_u32_e32 v63, 1, v51
	s_nop 0
	v_cndmask_b32_e64 v62, v51, v62, s[6:7]
	v_fma_f32 v51, -v63, v51, v47
	v_cmp_lt_f32_e64 s[6:7], 0, v51
	s_nop 1
	v_cndmask_b32_e64 v51, v62, v63, s[6:7]
	v_mul_f32_e32 v62, 0x37800000, v51
	v_cndmask_b32_e32 v51, v51, v62, vcc
	v_cmp_class_f32_e32 vcc, v47, v236
	s_nop 1
	v_cndmask_b32_e32 v47, v51, v47, vcc
	v_div_scale_f32 v51, s[6:7], v47, v47, 1.0
	v_rcp_f32_e32 v62, v51
	s_nop 0
	v_fma_f32 v63, -v51, v62, 1.0
	v_fmac_f32_e32 v62, v63, v62
	v_div_scale_f32 v63, vcc, 1.0, v47, 1.0
	v_mul_f32_e32 v68, v63, v62
	v_fma_f32 v69, -v51, v68, v63
	v_fmac_f32_e32 v68, v69, v62
	v_fma_f32 v51, -v51, v68, v63
	v_div_fmas_f32 v51, v51, v62, v68
	v_div_fixup_f32 v68, v51, v47, 1.0
	v_pk_mul_f32 v[58:59], v[58:59], v[68:69] op_sel_hi:[1,0]
	v_mov_b32_e32 v47, v48
	v_pk_mul_f32 v[62:63], v[66:67], v[68:69] op_sel_hi:[1,0]
	v_pk_mul_f32 v[60:61], v[60:61], v[68:69] op_sel_hi:[1,0]
	v_pk_mul_f32 v[46:47], v[46:47], v[68:69] op_sel_hi:[1,0]
	v_pk_fma_f32 v[58:59], v[6:7], v[58:59], v[14:15]
	v_pk_fma_f32 v[66:67], v[20:21], v[46:47], v[28:29]
	v_pk_fma_f32 v[46:47], v[2:3], v[60:61], v[10:11]
	v_pk_fma_f32 v[60:61], v[8:9], v[62:63], v[16:17]
	v_lshl_add_u64 v[62:63], s[8:9], 0, v[44:45]
	v_bfe_u32 v44, v58, 16, 1
	v_add3_u32 v44, v58, v44, s72
	v_bfe_u32 v45, v59, 16, 1
	v_lshrrev_b32_e32 v44, 16, v44
	v_add3_u32 v45, v59, v45, s72
	v_and_or_b32 v44, v45, s88, v44
	v_bfe_u32 v45, v60, 16, 1
	v_add3_u32 v45, v60, v45, s72
	v_bfe_u32 v48, v61, 16, 1
	v_lshrrev_b32_e32 v45, 16, v45
	v_add3_u32 v48, v61, v48, s72
	v_and_or_b32 v45, v48, s88, v45
	v_bfe_u32 v48, v46, 16, 1
	v_pk_mul_f32 v[64:65], v[64:65], v[68:69] op_sel_hi:[1,0]
	v_add3_u32 v46, v46, v48, s72
	v_bfe_u32 v48, v47, 16, 1
	v_pk_fma_f32 v[64:65], v[4:5], v[64:65], v[12:13]
	v_lshrrev_b32_e32 v46, 16, v46
	v_add3_u32 v47, v47, v48, s72
	v_and_or_b32 v46, v47, s88, v46
	v_bfe_u32 v47, v64, 16, 1
	v_add3_u32 v47, v64, v47, s72
	v_bfe_u32 v48, v65, 16, 1
	v_pk_mul_f32 v[54:55], v[54:55], v[68:69] op_sel_hi:[1,0]
	v_lshrrev_b32_e32 v47, 16, v47
	v_add3_u32 v48, v65, v48, s72
	v_pk_fma_f32 v[54:55], v[22:23], v[54:55], v[30:31]
	v_and_or_b32 v47, v48, s88, v47
	global_store_dwordx4 v[62:63], v[44:47], off
	v_pk_mul_f32 v[56:57], v[56:57], v[68:69] op_sel_hi:[1,0]
	v_mov_b32_e32 v51, v52
	v_bfe_u32 v44, v54, 16, 1
	v_add3_u32 v44, v54, v44, s72
	v_bfe_u32 v45, v55, 16, 1
	v_pk_fma_f32 v[56:57], v[24:25], v[56:57], v[32:33]
	v_lshrrev_b32_e32 v44, 16, v44
	v_add3_u32 v45, v55, v45, s72
	v_and_or_b32 v44, v45, s88, v44
	v_bfe_u32 v45, v56, 16, 1
	v_pk_mul_f32 v[50:51], v[50:51], v[68:69] op_sel_hi:[1,0]
	v_add3_u32 v45, v56, v45, s72
	v_bfe_u32 v46, v57, 16, 1
	v_pk_fma_f32 v[50:51], v[18:19], v[50:51], v[26:27]
	v_lshrrev_b32_e32 v45, 16, v45
	v_add3_u32 v46, v57, v46, s72
	v_and_or_b32 v45, v46, s88, v45
	v_bfe_u32 v46, v50, 16, 1
	v_add3_u32 v46, v50, v46, s72
	v_bfe_u32 v47, v51, 16, 1
	v_lshrrev_b32_e32 v46, 16, v46
	v_add3_u32 v47, v51, v47, s72
	v_and_or_b32 v46, v47, s88, v46
	v_bfe_u32 v47, v66, 16, 1
	v_add3_u32 v47, v66, v47, s72
	v_bfe_u32 v48, v67, 16, 1
	v_lshrrev_b32_e32 v47, 16, v47
	v_add3_u32 v48, v67, v48, s72
	v_and_or_b32 v47, v48, s88, v47
	global_store_dwordx4 v[62:63], v[44:47], off offset:1024
	s_cbranch_scc1 .LBB0_1881
	v_lshlrev_b32_e32 v57, 16, v35
	v_lshlrev_b32_e32 v56, 16, v34
	v_and_b32_e32 v35, 0xffff0000, v35
	v_and_b32_e32 v34, 0xffff0000, v34
	v_pk_add_f32 v[58:59], v[56:57], v[34:35]
	v_lshlrev_b32_e32 v50, 16, v41
	v_and_b32_e32 v54, 0xffff0000, v41
	v_add_f32_e32 v41, v58, v59
	v_lshlrev_b32_e32 v59, 16, v37
	v_lshlrev_b32_e32 v58, 16, v36
	v_and_b32_e32 v37, 0xffff0000, v37
	v_and_b32_e32 v36, 0xffff0000, v36
	v_pk_add_f32 v[60:61], v[58:59], v[36:37]
	v_lshlrev_b32_e32 v44, 16, v38
	v_and_b32_e32 v45, 0xffff0000, v38
	v_lshlrev_b32_e32 v38, 16, v39
	v_and_b32_e32 v39, 0xffff0000, v39
	v_pk_add_f32 v[60:61], v[60:61], v[60:61] op_sel_hi:[0,1]
	v_lshlrev_b32_e32 v46, 16, v40
	v_and_b32_e32 v40, 0xffff0000, v40
	v_add_f32_e32 v55, 0, v41
	v_add_f32_e32 v47, v44, v45
	v_add_f32_e32 v41, v38, v39
	v_mov_b32_e32 v51, v61
	v_pk_add_f32 v[62:63], v[46:47], v[40:41]
	v_pk_add_f32 v[60:61], v[50:51], v[54:55]
	s_ashr_i32 s5, s4, 31
	v_pk_add_f32 v[60:61], v[62:63], v[60:61]
	s_lshl_b64 s[4:5], s[4:5], 11
	v_add_f32_e32 v41, v60, v61
	s_nop 1
	v_add_f32_dpp v41, v41, v41 quad_perm:[1,0,3,2] row_mask:0xf bank_mask:0xf
	s_nop 1
	v_add_f32_dpp v41, v41, v41 quad_perm:[2,3,0,1] row_mask:0xf bank_mask:0xf
	s_nop 1
	v_add_f32_dpp v41, v41, v41 row_half_mirror row_mask:0xf bank_mask:0xf
	s_nop 1
	v_add_f32_dpp v41, v41, v41 row_mirror row_mask:0xf bank_mask:0xf
	v_mov_b32_e32 v47, v41
	v_mov_b32_e32 v72, v41
	s_nop 1
	v_permlane16_swap_b32_e32 v47, v72
	s_nop 1
	v_add_f32_e32 v41, v47, v72
	v_mov_b32_e32 v47, v41
	v_mov_b32_e32 v72, v41
	s_nop 1
	v_permlane32_swap_b32_e32 v47, v72
	s_nop 1
	v_add_f32_e32 v41, v47, v72
	v_fmac_f32_e32 v34, 0xba800000, v41
; #define GAS __attribute__((address_space(1)))
; __device__ __forceinline__ unsigned pk2(float lo, float hi) { return f2bf(lo) | (f2bf(hi) << 16); }
; #define WSB(F, off) ((bf16*)(wsq((F).ws) + (off)))
; __device__ __forceinline__ void ln_rows(const Frame& F, int idx, bool final_out, int row_lo, int row_hi, int gw0, int NGW, bool comb = false) {
;     ...
;         const float mean = wave_sum(s) * (1.f / D); float s2 = 0.f;
; #pragma unroll
;         for (int j = 0; j < 4; ++j) { v[j] = v[j] - mean; s2 += (v[j].x * v[j].x + v[j].y * v[j].y) + (v[j].z * v[j].z + v[j].w * v[j].w); }
;         const float rstd = 1.f / sqrtf(wave_sum(s2) * (1.f / D) + LN_EPS);
; #pragma unroll
;         for (int j = 0; j < 4; ++j) v[j] = v[j] * rstd * gv[j] + bv[j];
;         if (!final_out) { GAS v4u* o = (GAS v4u*)(WSB(F, WS_HB) + (size_t)m * D) + tc.lane;
; #pragma unroll
;             for (int j = 0; j < 2; ++j) o[64 * j] = (v4u){pk2(v[2 * j].x, v[2 * j].y), pk2(v[2 * j].z, v[2 * j].w), pk2(v[2 * j + 1].x, v[2 * j + 1].y), pk2(v[2 * j + 1].z, v[2 * j + 1].w)}; }
	v_fmac_f32_e32 v35, 0xba800000, v41
	v_fmac_f32_e32 v57, 0xba800000, v41
	v_fmac_f32_e32 v56, 0xba800000, v41
	v_mov_b32_e32 v60, v57
	v_mov_b32_e32 v61, v35
	v_mov_b32_e32 v57, v34
	v_pk_mul_f32 v[62:63], v[60:61], v[60:61]
	v_pk_mul_f32 v[34:35], v[56:57], v[56:57]
	v_fmac_f32_e32 v36, 0xba800000, v41
	v_pk_mov_b32 v[64:65], v[34:35], v[62:63] op_sel:[1,0]
	v_mov_b32_e32 v35, v63
	v_fmac_f32_e32 v37, 0xba800000, v41
	v_fmac_f32_e32 v59, 0xba800000, v41
	v_pk_add_f32 v[34:35], v[64:65], v[34:35]
	v_fmac_f32_e32 v58, 0xba800000, v41
	v_mov_b32_e32 v62, v59
	v_mov_b32_e32 v63, v37
	v_mov_b32_e32 v59, v36
	v_pk_add_f32 v[34:35], v[34:35], v[34:35] op_sel_hi:[0,1]
	v_pk_mul_f32 v[64:65], v[62:63], v[62:63]
	v_pk_mul_f32 v[36:37], v[58:59], v[58:59]
	v_fmac_f32_e32 v44, 0xba800000, v41
	v_pk_mov_b32 v[66:67], v[36:37], v[64:65] op_sel:[1,0]
	v_mov_b32_e32 v37, v65
	v_fmac_f32_e32 v45, 0xba800000, v41
	v_fmac_f32_e32 v38, 0xba800000, v41
	v_mul_f32_e32 v34, v44, v44
	v_pk_add_f32 v[36:37], v[66:67], v[36:37]
	v_fmac_f32_e32 v39, 0xba800000, v41
	v_pk_fma_f32 v[64:65], v[44:45], v[44:45], v[34:35] op_sel_hi:[1,1,0]
	v_mul_f32_e32 v34, v38, v38
	v_pk_add_f32 v[36:37], v[36:37], v[36:37] op_sel_hi:[0,1]
	v_pk_fma_f32 v[66:67], v[38:39], v[38:39], v[34:35] op_sel_hi:[1,1,0]
	v_fmac_f32_e32 v54, 0xba800000, v41
	v_fmac_f32_e32 v50, 0xba800000, v41
	v_fmac_f32_e32 v40, 0xba800000, v41
	v_fmac_f32_e32 v46, 0xba800000, v41
	v_mul_f32_e32 v64, v46, v46
	v_mul_f32_e32 v66, v40, v40
	v_mul_f32_e32 v34, v50, v50
	v_mul_f32_e32 v36, v54, v54
	v_pk_add_f32 v[64:65], v[64:65], v[66:67]
	v_pk_add_f32 v[34:35], v[34:35], v[36:37]
	v_mov_b32_e32 v47, v40
	v_pk_add_f32 v[34:35], v[64:65], v[34:35]
	v_mov_b32_e32 v51, v54
	v_add_f32_e32 v34, v34, v35
	s_nop 1
	v_add_f32_dpp v34, v34, v34 quad_perm:[1,0,3,2] row_mask:0xf bank_mask:0xf
	s_nop 1
	v_add_f32_dpp v34, v34, v34 quad_perm:[2,3,0,1] row_mask:0xf bank_mask:0xf
	s_nop 1
	v_add_f32_dpp v34, v34, v34 row_half_mirror row_mask:0xf bank_mask:0xf
	s_nop 1
	v_add_f32_dpp v34, v34, v34 row_mirror row_mask:0xf bank_mask:0xf
	v_mov_b32_e32 v72, v34
	v_mov_b32_e32 v71, v34
	s_nop 1
	v_permlane16_swap_b32_e32 v72, v71
	s_nop 1
	v_add_f32_e32 v34, v72, v71
	v_mov_b32_e32 v72, v34
	v_mov_b32_e32 v71, v34
	s_nop 1
	v_permlane32_swap_b32_e32 v72, v71
	s_nop 1
	v_add_f32_e32 v1, v72, v71
	v_fmamk_f32 v1, v1, 0x3a800000, v235
	v_mul_f32_e32 v34, 0x4f800000, v1
	v_cmp_gt_f32_e32 vcc, s89, v1
	s_nop 1
	v_cndmask_b32_e32 v1, v1, v34, vcc
	v_sqrt_f32_e32 v34, v1
	s_nop 0
	v_add_u32_e32 v35, -1, v34
	v_fma_f32 v36, -v35, v34, v1
	v_cmp_ge_f32_e64 s[6:7], 0, v36
	v_add_u32_e32 v36, 1, v34
	s_nop 0
	v_cndmask_b32_e64 v35, v34, v35, s[6:7]
	v_fma_f32 v34, -v36, v34, v1
	v_cmp_lt_f32_e64 s[6:7], 0, v34
	s_nop 1
	v_cndmask_b32_e64 v34, v35, v36, s[6:7]
	v_mul_f32_e32 v35, 0x37800000, v34
	v_cndmask_b32_e32 v34, v34, v35, vcc
	v_cmp_class_f32_e32 vcc, v1, v236
	s_nop 1
	v_cndmask_b32_e32 v1, v34, v1, vcc
	v_div_scale_f32 v34, s[6:7], v1, v1, 1.0
	v_rcp_f32_e32 v35, v34
	s_mov_b64 s[6:7], s[46:47]
	s_add_u32 s4, s6, s4
	v_fma_f32 v36, -v34, v35, 1.0
	v_fmac_f32_e32 v35, v36, v35
	v_div_scale_f32 v36, vcc, 1.0, v1, 1.0
	v_mul_f32_e32 v37, v36, v35
	v_fma_f32 v41, -v34, v37, v36
	v_fmac_f32_e32 v37, v41, v35
	v_fma_f32 v34, -v34, v37, v36
	v_div_fmas_f32 v34, v34, v35, v37
	v_div_fixup_f32 v34, v34, v1, 1.0
	v_pk_mul_f32 v[36:37], v[56:57], v[34:35] op_sel_hi:[1,0]
	v_pk_mul_f32 v[48:49], v[60:61], v[34:35] op_sel_hi:[1,0]
	v_pk_mul_f32 v[52:53], v[58:59], v[34:35] op_sel_hi:[1,0]
	v_pk_mul_f32 v[56:57], v[62:63], v[34:35] op_sel_hi:[1,0]
	v_pk_mul_f32 v[44:45], v[44:45], v[34:35] op_sel_hi:[1,0]
	v_pk_mul_f32 v[38:39], v[38:39], v[34:35] op_sel_hi:[1,0]
	v_pk_mul_f32 v[40:41], v[46:47], v[34:35] op_sel_hi:[1,0]
	v_pk_mul_f32 v[34:35], v[50:51], v[34:35] op_sel_hi:[1,0]
	v_pk_fma_f32 v[48:49], v[8:9], v[48:49], v[16:17]
	v_pk_fma_f32 v[46:47], v[20:21], v[34:35], v[28:29]
	v_pk_fma_f32 v[34:35], v[6:7], v[36:37], v[14:15]
	v_pk_fma_f32 v[52:53], v[2:3], v[52:53], v[10:11]
	v_bfe_u32 v1, v34, 16, 1
	v_add3_u32 v1, v34, v1, s72
	v_bfe_u32 v34, v35, 16, 1
	v_lshrrev_b32_e32 v1, 16, v1
	v_add3_u32 v34, v35, v34, s72
	v_and_or_b32 v34, v34, s88, v1
	v_bfe_u32 v1, v48, 16, 1
	v_add3_u32 v1, v48, v1, s72
	v_bfe_u32 v35, v49, 16, 1
	v_lshrrev_b32_e32 v1, 16, v1
	v_add3_u32 v35, v49, v35, s72
	v_and_or_b32 v35, v35, s88, v1
	v_bfe_u32 v1, v52, 16, 1
	v_add3_u32 v1, v52, v1, s72
	v_bfe_u32 v36, v53, 16, 1
	v_pk_fma_f32 v[50:51], v[4:5], v[56:57], v[12:13]
	s_addc_u32 s5, s7, s5
	v_lshrrev_b32_e32 v1, 16, v1
	v_add3_u32 v36, v53, v36, s72
	v_lshl_add_u64 v[54:55], v[42:43], 4, s[4:5]
	s_mov_b64 s[4:5], 0x8200000
	v_and_or_b32 v36, v36, s88, v1
	v_bfe_u32 v1, v50, 16, 1
	v_lshl_add_u64 v[56:57], v[54:55], 0, s[4:5]
	v_add3_u32 v1, v50, v1, s72
	v_bfe_u32 v37, v51, 16, 1
	s_mov_b32 s4, 0x8200000
	v_pk_fma_f32 v[44:45], v[22:23], v[44:45], v[30:31]
	v_lshrrev_b32_e32 v1, 16, v1
	v_add3_u32 v37, v51, v37, s72
	v_add_co_u32_e32 v48, vcc, s4, v54
	v_and_or_b32 v37, v37, s88, v1
	s_nop 0
	v_addc_co_u32_e32 v49, vcc, 0, v55, vcc
	v_bfe_u32 v1, v44, 16, 1
	global_store_dwordx4 v[48:49], v[34:37], off
	v_add3_u32 v1, v44, v1, s72
	v_pk_fma_f32 v[38:39], v[24:25], v[38:39], v[32:33]
	v_bfe_u32 v34, v45, 16, 1
	v_lshrrev_b32_e32 v1, 16, v1
	v_add3_u32 v34, v45, v34, s72
	v_and_or_b32 v34, v34, s88, v1
	v_bfe_u32 v1, v38, 16, 1
	v_add3_u32 v1, v38, v1, s72
	v_bfe_u32 v35, v39, 16, 1
	v_pk_fma_f32 v[40:41], v[18:19], v[40:41], v[26:27]
	v_lshrrev_b32_e32 v1, 16, v1
	v_add3_u32 v35, v39, v35, s72
	v_and_or_b32 v35, v35, s88, v1
	v_bfe_u32 v1, v40, 16, 1
	v_add3_u32 v1, v40, v1, s72
	v_bfe_u32 v36, v41, 16, 1
	v_lshrrev_b32_e32 v1, 16, v1
	v_add3_u32 v36, v41, v36, s72
	v_and_or_b32 v36, v36, s88, v1
	v_bfe_u32 v1, v46, 16, 1
	v_add3_u32 v1, v46, v1, s72
	v_bfe_u32 v37, v47, 16, 1
	v_lshrrev_b32_e32 v1, 16, v1
	v_add3_u32 v37, v47, v37, s72
	v_and_or_b32 v37, v37, s88, v1
	global_store_dwordx4 v[56:57], v[34:37], off offset:1024
	s_branch .LBB0_1881

; #define GAS __attribute__((address_space(1)))
; #define WSB(F, off) ((bf16*)(wsq((F).ws) + (off)))
; __device__ __forceinline__ void ln_rows(const Frame& F, int idx, bool final_out, int row_lo, int row_hi, int gw0, int NGW, bool comb = false) {
;     ...
;         for (int r = 0; r < 2; ++r) { const int m = (r == 0 || two) ? m0 + r * NGW : m0; const GAS v4u* yr = (const GAS v4u*)(WSB(F, comb ? WS_HB : WS_YB) + (size_t)m * D) + tc.lane; w[r][0] = yr[0]; w[r][1] = yr[64]; }
; #pragma unroll
;         for (int r = 0; r < 2; ++r) { const int m = m0 + r * NGW; if (r == 1 && !two) break;
;         f32x4 v[4]; float s = 0.f;
; #pragma unroll
;         for (int j = 0; j < 2; ++j) { const v4u x = w[r][j]; v[2 * j] = (f32x4){bflo(x.x), bfhi(x.x), bflo(x.y), bfhi(x.y)}; v[2 * j + 1] = (f32x4){bflo(x.z), bfhi(x.z), bflo(x.w), bfhi(x.w)}; }
;         if (comb) {
;             const GAS f32x4* pa = (const GAS f32x4*)((const float*)WSB(F, WS_ACT) + (size_t)(m - MP) * D) + 2 * tc.lane; const GAS f32x4* pb = pa + (size_t)512 * D / 4;
; #pragma unroll
;             for (int j = 0; j < 2; ++j) { v[2 * j] = v[2 * j] * ALPHA + (pa[128 * j] + pb[128 * j]) * 0.5f; v[2 * j + 1] = v[2 * j + 1] * ALPHA + (pa[128 * j + 1] + pb[128 * j + 1]) * 0.5f; } }
; #pragma unroll
;         for (int j = 0; j < 4; ++j) s += (v[j].x + v[j].y) + (v[j].z + v[j].w);
;         const float mean = wave_sum(s) * (1.f / D); float s2 = 0.f;
.LBB0_2169:
	v_readlane_b32 s11, v253, 7
	s_mov_b64 s[4:5], s[46:47]
	s_add_i32 s10, s11, s16
	s_add_u32 s4, s4, s2
	s_addc_u32 s5, s5, s3
	v_lshlrev_b64 v[34:35], 4, v[58:59]
	v_lshl_add_u64 v[36:37], s[4:5], 0, v[34:35]
	global_load_dwordx4 v[42:45], v[36:37], off
	global_load_dwordx4 v[46:49], v[36:37], off offset:1024
	s_cmp_lt_i32 s10, 0x10200
	s_cselect_b64 s[6:7], -1, 0
	s_and_b64 s[4:5], s[6:7], exec
	s_cselect_b32 s4, s11, 0
	s_add_i32 s4, s4, s16
	s_ashr_i32 s5, s4, 31
	s_mov_b64 s[12:13], s[46:47]
	s_lshl_b64 s[4:5], s[4:5], 11
	s_add_u32 s4, s12, s4
	s_addc_u32 s5, s13, s5
	v_lshl_add_u64 v[34:35], s[4:5], 0, v[34:35]
	s_mov_b64 s[4:5], 0x8200000
	v_lshl_add_u64 v[36:37], v[34:35], 0, s[4:5]
	s_mov_b32 s4, 0x8200000
	v_add_co_u32_e32 v34, vcc, s4, v34
	s_add_i32 s12, s16, 0xffff0000
	s_nop 0
	v_addc_co_u32_e32 v35, vcc, 0, v35, vcc
	s_mov_b64 s[4:5], s[46:47]
	s_ashr_i32 s13, s12, 31
	global_load_dwordx4 v[38:41], v[34:35], off
	s_nop 0
	global_load_dwordx4 v[34:37], v[36:37], off offset:1024
	s_lshl_b64 s[14:15], s[12:13], 12
	s_add_u32 s4, s4, s14
	s_addc_u32 s5, s5, s15
	v_lshl_add_u64 v[78:79], v[60:61], 4, s[4:5]
	s_mov_b64 s[4:5], 0x10300000
	v_lshl_add_u64 v[80:81], v[78:79], 0, s[4:5]
	s_mov_b64 s[4:5], 0x10500000
	v_lshl_add_u64 v[62:63], v[78:79], 0, s[4:5]
	s_mov_b32 s4, 0x10300000
	v_readlane_b32 s18, v252, 6
	v_readlane_b32 s19, v252, 7
	s_mov_b64 s[14:15], -1
	s_waitcnt vmcnt(0)
	v_lshlrev_b32_e32 v66, 16, v42
	v_and_b32_e32 v67, 0xffff0000, v42
	v_add_co_u32_e32 v42, vcc, s4, v78
	v_lshlrev_b32_e32 v68, 16, v43
	v_and_b32_e32 v69, 0xffff0000, v43
	v_addc_co_u32_e32 v43, vcc, 0, v79, vcc
	s_mov_b32 s4, 0x10500000
	v_add_co_u32_e32 v82, vcc, s4, v78
	v_lshlrev_b32_e32 v70, 16, v44
	s_nop 0
	v_addc_co_u32_e32 v83, vcc, 0, v79, vcc
	v_and_b32_e32 v71, 0xffff0000, v44
	v_lshlrev_b32_e32 v72, 16, v45
	v_and_b32_e32 v73, 0xffff0000, v45
	v_lshlrev_b32_e32 v74, 16, v46
	v_and_b32_e32 v75, 0xffff0000, v46
	v_lshlrev_b32_e32 v76, 16, v47
	v_and_b32_e32 v77, 0xffff0000, v47
	v_lshlrev_b32_e32 v54, 16, v48
	v_and_b32_e32 v55, 0xffff0000, v48
	v_lshlrev_b32_e32 v56, 16, v49
	v_and_b32_e32 v57, 0xffff0000, v49
	global_load_dwordx4 v[42:45], v[42:43], off
	s_nop 0
	global_load_dwordx4 v[46:49], v[80:81], off offset:16
	global_load_dwordx4 v[50:53], v[82:83], off
	s_nop 0
	global_load_dwordx4 v[62:65], v[62:63], off offset:16
	s_mov_b64 s[4:5], 0x10500800
	s_waitcnt vmcnt(1)
	v_pk_add_f32 v[44:45], v[44:45], v[52:53]
	s_waitcnt vmcnt(0)
	v_pk_add_f32 v[46:47], v[46:47], v[62:63]
	v_pk_add_f32 v[42:43], v[42:43], v[50:51]
	v_pk_add_f32 v[48:49], v[48:49], v[64:65]
	v_pk_mul_f32 v[46:47], v[46:47], 0.5 op_sel_hi:[1,0]
	v_pk_mul_f32 v[44:45], v[44:45], 0.5 op_sel_hi:[1,0]
	v_pk_mul_f32 v[50:51], v[42:43], 0.5 op_sel_hi:[1,0]
	v_pk_mul_f32 v[48:49], v[48:49], 0.5 op_sel_hi:[1,0]
	v_pk_fma_f32 v[46:47], v[70:71], s[96:97], v[46:47] op_sel_hi:[1,0,1]
	v_lshl_add_u64 v[70:71], v[78:79], 0, s[4:5]
	v_pk_fma_f32 v[42:43], v[68:69], s[96:97], v[44:45] op_sel_hi:[1,0,1]
	v_pk_fma_f32 v[44:45], v[66:67], s[96:97], v[50:51] op_sel_hi:[1,0,1]
	v_pk_fma_f32 v[48:49], v[72:73], s[96:97], v[48:49] op_sel_hi:[1,0,1]
	global_load_dwordx4 v[62:65], v[80:81], off offset:2064
	global_load_dwordx4 v[50:53], v[80:81], off offset:2048
	global_load_dwordx4 v[66:69], v[82:83], off offset:2048
	s_nop 0
	global_load_dwordx4 v[70:73], v[70:71], off offset:16
	s_waitcnt vmcnt(1)
	v_pk_add_f32 v[52:53], v[52:53], v[68:69]
	s_waitcnt vmcnt(0)
	v_pk_add_f32 v[64:65], v[64:65], v[72:73]
	v_pk_add_f32 v[62:63], v[62:63], v[70:71]
	v_pk_add_f32 v[50:51], v[50:51], v[66:67]
	v_pk_mul_f32 v[64:65], v[64:65], 0.5 op_sel_hi:[1,0]
	v_pk_mul_f32 v[62:63], v[62:63], 0.5 op_sel_hi:[1,0]
	v_pk_mul_f32 v[52:53], v[52:53], 0.5 op_sel_hi:[1,0]
	v_pk_mul_f32 v[66:67], v[50:51], 0.5 op_sel_hi:[1,0]
	v_pk_fma_f32 v[56:57], v[56:57], s[96:97], v[64:65] op_sel_hi:[1,0,1]
	v_pk_fma_f32 v[54:55], v[54:55], s[96:97], v[62:63] op_sel_hi:[1,0,1]
	v_pk_mov_b32 v[62:63], v[44:45], v[42:43] op_sel:[1,0]
	v_mov_b32_e32 v64, v44
	v_mov_b32_e32 v65, v43
	v_pk_fma_f32 v[50:51], v[76:77], s[96:97], v[52:53] op_sel_hi:[1,0,1]
	v_pk_fma_f32 v[52:53], v[74:75], s[96:97], v[66:67] op_sel_hi:[1,0,1]
	v_pk_add_f32 v[62:63], v[62:63], v[64:65]
	v_pk_mov_b32 v[64:65], v[46:47], v[48:49] op_sel:[1,0]
	v_mov_b32_e32 v66, v46
	v_mov_b32_e32 v67, v49
	v_pk_add_f32 v[64:65], v[64:65], v[66:67]
	v_add_f32_e32 v1, v62, v63
	v_pk_add_f32 v[64:65], v[64:65], v[64:65] op_sel:[0,1] op_sel_hi:[1,0]
	v_add_f32_e32 v62, 0, v1
	v_add_f32_e32 v66, v52, v53
	v_add_f32_e32 v68, v50, v51
	v_mov_b32_e32 v63, v54
	v_mov_b32_e32 v65, v55
	v_mov_b32_e32 v67, v56
	v_mov_b32_e32 v69, v57
	v_and_b32_e32 v1, 64, v239
	v_pk_add_f32 v[62:63], v[62:63], v[64:65]
	v_pk_add_f32 v[64:65], v[66:67], v[68:69]
	v_add_u32_e32 v66, 64, v1
	v_xor_b32_e32 v1, 1, v239
	v_cmp_lt_i32_e32 vcc, v1, v66
	v_pk_add_f32 v[62:63], v[62:63], v[64:65]
	s_nop 0
	v_cndmask_b32_e32 v1, v239, v1, vcc
	v_add_f32_e32 v62, v62, v63
	v_lshlrev_b32_e32 v1, 2, v1
	s_nop 1
	v_add_f32_dpp v62, v62, v62 quad_perm:[1,0,3,2] row_mask:0xf bank_mask:0xf
	s_nop 1
	v_add_f32_dpp v62, v62, v62 quad_perm:[2,3,0,1] row_mask:0xf bank_mask:0xf
	s_nop 1
	v_add_f32_dpp v62, v62, v62 row_half_mirror row_mask:0xf bank_mask:0xf
	s_nop 1
	v_add_f32_dpp v62, v62, v62 row_mirror row_mask:0xf bank_mask:0xf
	v_mov_b32_e32 v63, v62
	v_mov_b32_e32 v64, v62
	s_nop 1
	v_permlane16_swap_b32_e32 v63, v64
	s_nop 1
	v_add_f32_e32 v62, v63, v64
	v_mov_b32_e32 v63, v62
	v_mov_b32_e32 v64, v62
	s_nop 1
	v_permlane32_swap_b32_e32 v63, v64
	s_nop 1
	v_add_f32_e32 v67, v63, v64
	v_xor_b32_e32 v62, 2, v239
; #define GAS __attribute__((address_space(1)))
; __device__ __forceinline__ unsigned pk2(float lo, float hi) { return f2bf(lo) | (f2bf(hi) << 16); }
; #define WSB(F, off) ((bf16*)(wsq((F).ws) + (off)))
; __device__ __forceinline__ void ln_rows(const Frame& F, int idx, bool final_out, int row_lo, int row_hi, int gw0, int NGW, bool comb = false) {
;     ...
;         const float mean = wave_sum(s) * (1.f / D); float s2 = 0.f;
; #pragma unroll
;         for (int j = 0; j < 4; ++j) { v[j] = v[j] - mean; s2 += (v[j].x * v[j].x + v[j].y * v[j].y) + (v[j].z * v[j].z + v[j].w * v[j].w); }
;         const float rstd = 1.f / sqrtf(wave_sum(s2) * (1.f / D) + LN_EPS);
; #pragma unroll
;         for (int j = 0; j < 4; ++j) v[j] = v[j] * rstd * gv[j] + bv[j];
;         if (!final_out) { GAS v4u* o = (GAS v4u*)(WSB(F, WS_HB) + (size_t)m * D) + tc.lane;
; #pragma unroll
;             for (int j = 0; j < 2; ++j) o[64 * j] = (v4u){pk2(v[2 * j].x, v[2 * j].y), pk2(v[2 * j].z, v[2 * j].w), pk2(v[2 * j + 1].x, v[2 * j + 1].y), pk2(v[2 * j + 1].z, v[2 * j + 1].w)}; }
	v_cmp_lt_i32_e32 vcc, v62, v66
	s_nop 1
	v_cndmask_b32_e32 v62, v239, v62, vcc
	v_lshlrev_b32_e32 v62, 2, v62
	v_xor_b32_e32 v63, 4, v239
	v_cmp_lt_i32_e32 vcc, v63, v66
	s_nop 1
	v_cndmask_b32_e32 v63, v239, v63, vcc
	v_lshlrev_b32_e32 v63, 2, v63
	v_xor_b32_e32 v64, 8, v239
	v_cmp_lt_i32_e32 vcc, v64, v66
	s_nop 1
	v_cndmask_b32_e32 v64, v239, v64, vcc
	v_lshlrev_b32_e32 v64, 2, v64
	v_xor_b32_e32 v65, 16, v239
	v_cmp_lt_i32_e32 vcc, v65, v66
	s_nop 1
	v_cndmask_b32_e32 v65, v239, v65, vcc
	v_lshlrev_b32_e32 v65, 2, v65
	v_xor_b32_e32 v68, 32, v239
	v_cmp_lt_i32_e32 vcc, v68, v66
	s_nop 1
	v_cndmask_b32_e32 v66, v239, v68, vcc
	v_lshlrev_b32_e32 v66, 2, v66
	v_fmamk_f32 v45, v67, 0xba800000, v45
	v_fmac_f32_e32 v44, 0xba800000, v67
	v_fmamk_f32 v43, v67, 0xba800000, v43
	v_fmac_f32_e32 v42, 0xba800000, v67
	v_pk_mul_f32 v[68:69], v[42:43], v[42:43]
	v_pk_mul_f32 v[70:71], v[44:45], v[44:45]
	v_fmamk_f32 v47, v67, 0xba800000, v47
	v_pk_mov_b32 v[72:73], v[70:71], v[68:69] op_sel:[1,0]
	v_mov_b32_e32 v71, v69
	v_pk_add_f32 v[68:69], v[72:73], v[70:71]
	v_fmac_f32_e32 v46, 0xba800000, v67
	v_fmamk_f32 v49, v67, 0xba800000, v49
	v_fmac_f32_e32 v48, 0xba800000, v67
	v_pk_add_f32 v[68:69], v[68:69], v[68:69] op_sel_hi:[0,1]
	v_pk_mul_f32 v[70:71], v[48:49], v[48:49]
	v_pk_mul_f32 v[72:73], v[46:47], v[46:47]
	v_fmac_f32_e32 v52, 0xba800000, v67
	v_pk_mov_b32 v[74:75], v[72:73], v[70:71] op_sel:[1,0]
	v_mov_b32_e32 v73, v71
	v_fmamk_f32 v53, v67, 0xba800000, v53
	v_fmac_f32_e32 v50, 0xba800000, v67
	v_mul_f32_e32 v68, v52, v52
	v_pk_add_f32 v[70:71], v[74:75], v[72:73]
	v_fmamk_f32 v51, v67, 0xba800000, v51
	v_pk_fma_f32 v[72:73], v[52:53], v[52:53], v[68:69] op_sel_hi:[1,1,0]
	v_mul_f32_e32 v68, v50, v50
	v_pk_add_f32 v[70:71], v[70:71], v[70:71] op_sel_hi:[0,1]
	v_pk_fma_f32 v[74:75], v[50:51], v[50:51], v[68:69] op_sel_hi:[1,1,0]
	v_fmamk_f32 v57, v67, 0xba800000, v57
	v_fmac_f32_e32 v56, 0xba800000, v67
	v_fmamk_f32 v55, v67, 0xba800000, v55
	v_fmac_f32_e32 v54, 0xba800000, v67
	v_mul_f32_e32 v72, v54, v54
	v_mul_f32_e32 v74, v55, v55
	v_mul_f32_e32 v68, v56, v56
	v_mul_f32_e32 v70, v57, v57
	v_pk_add_f32 v[72:73], v[72:73], v[74:75]
	v_pk_add_f32 v[68:69], v[68:69], v[70:71]
	s_nop 0
	v_pk_add_f32 v[68:69], v[72:73], v[68:69]
	s_nop 0
	v_add_f32_e32 v67, v68, v69
	s_nop 1
	v_add_f32_dpp v67, v67, v67 quad_perm:[1,0,3,2] row_mask:0xf bank_mask:0xf
	s_nop 1
	v_add_f32_dpp v67, v67, v67 quad_perm:[2,3,0,1] row_mask:0xf bank_mask:0xf
	s_nop 1
	v_add_f32_dpp v67, v67, v67 row_half_mirror row_mask:0xf bank_mask:0xf
	s_nop 1
	v_add_f32_dpp v67, v67, v67 row_mirror row_mask:0xf bank_mask:0xf
	v_mov_b32_e32 v68, v67
	v_mov_b32_e32 v66, v67
	s_nop 1
	v_permlane16_swap_b32_e32 v68, v66
	s_nop 1
	v_add_f32_e32 v67, v68, v66
	v_mov_b32_e32 v68, v67
	v_mov_b32_e32 v66, v67
	s_nop 1
	v_permlane32_swap_b32_e32 v68, v66
	s_nop 1
	v_add_f32_e32 v67, v68, v66
	v_fmamk_f32 v67, v67, 0x3a800000, v235
	v_cmp_gt_f32_e32 vcc, s89, v67
	v_mul_f32_e32 v68, 0x4f800000, v67
	s_nop 0
	v_cndmask_b32_e32 v67, v67, v68, vcc
	v_sqrt_f32_e32 v68, v67
	s_nop 0
	v_add_u32_e32 v69, -1, v68
	v_fma_f32 v70, -v69, v68, v67
	v_cmp_ge_f32_e64 s[4:5], 0, v70
	v_add_u32_e32 v70, 1, v68
	s_nop 0
	v_cndmask_b32_e64 v69, v68, v69, s[4:5]
	v_fma_f32 v68, -v70, v68, v67
	v_cmp_lt_f32_e64 s[4:5], 0, v68
	s_nop 1
	v_cndmask_b32_e64 v68, v69, v70, s[4:5]
	v_mul_f32_e32 v69, 0x37800000, v68
	v_cndmask_b32_e32 v68, v68, v69, vcc
	v_cmp_class_f32_e32 vcc, v67, v236
	s_nop 1
	v_cndmask_b32_e32 v67, v68, v67, vcc
	v_div_scale_f32 v68, s[4:5], v67, v67, 1.0
	v_rcp_f32_e32 v69, v68
	s_nop 0
	v_fma_f32 v70, -v68, v69, 1.0
	v_fmac_f32_e32 v69, v70, v69
	v_div_scale_f32 v70, vcc, 1.0, v67, 1.0
	v_mul_f32_e32 v71, v70, v69
	v_fma_f32 v72, -v68, v71, v70
	v_fmac_f32_e32 v71, v72, v69
	v_fma_f32 v68, -v68, v71, v70
	v_div_fmas_f32 v68, v68, v69, v71
	v_div_fixup_f32 v68, v68, v67, 1.0
	v_pk_mul_f32 v[70:71], v[44:45], v[68:69] op_sel_hi:[1,0]
	v_pk_mul_f32 v[42:43], v[42:43], v[68:69] op_sel_hi:[1,0]
	v_pk_mul_f32 v[46:47], v[46:47], v[68:69] op_sel_hi:[1,0]
	v_pk_fma_f32 v[44:45], v[8:9], v[42:43], v[16:17]
	v_pk_fma_f32 v[42:43], v[6:7], v[70:71], v[14:15]
	v_pk_mul_f32 v[48:49], v[48:49], v[68:69] op_sel_hi:[1,0]
	v_pk_mul_f32 v[70:71], v[52:53], v[68:69] op_sel_hi:[1,0]
	v_pk_mul_f32 v[50:51], v[50:51], v[68:69] op_sel_hi:[1,0]
	v_pk_mul_f32 v[54:55], v[54:55], v[68:69] op_sel_hi:[1,0]
	v_pk_mul_f32 v[56:57], v[56:57], v[68:69] op_sel_hi:[1,0]
	v_cndmask_b32_e64 v67, 0, 1, s[18:19]
	v_pk_fma_f32 v[48:49], v[4:5], v[48:49], v[12:13]
	v_pk_fma_f32 v[46:47], v[2:3], v[46:47], v[10:11]
	v_pk_fma_f32 v[52:53], v[24:25], v[50:51], v[32:33]
	v_pk_fma_f32 v[50:51], v[22:23], v[70:71], v[30:31]
	v_pk_fma_f32 v[56:57], v[20:21], v[56:57], v[28:29]
	v_pk_fma_f32 v[54:55], v[18:19], v[54:55], v[26:27]
	v_cmp_ne_u32_e64 s[4:5], 1, v67
	s_andn2_b64 vcc, exec, s[18:19]
	s_cbranch_vccnz .LBB0_2171
	v_bfe_u32 v67, v42, 16, 1
	v_add3_u32 v67, v42, v67, s72
	v_bfe_u32 v68, v43, 16, 1
	v_lshrrev_b32_e32 v67, 16, v67
	v_add3_u32 v68, v43, v68, s72
	v_and_or_b32 v68, v68, s88, v67
	v_bfe_u32 v67, v44, 16, 1
	v_add3_u32 v67, v44, v67, s72
	v_bfe_u32 v69, v45, 16, 1
	v_lshrrev_b32_e32 v67, 16, v67
	v_add3_u32 v69, v45, v69, s72
	v_and_or_b32 v69, v69, s88, v67
	v_bfe_u32 v67, v46, 16, 1
	v_add3_u32 v67, v46, v67, s72
	v_bfe_u32 v70, v47, 16, 1
	s_mov_b64 s[14:15], s[46:47]
	v_lshrrev_b32_e32 v67, 16, v67
	v_add3_u32 v70, v47, v70, s72
	v_and_or_b32 v70, v70, s88, v67
	v_bfe_u32 v67, v48, 16, 1
	s_add_u32 s14, s14, s2
	v_add3_u32 v67, v48, v67, s72
	v_bfe_u32 v71, v49, 16, 1
	s_addc_u32 s15, s15, s3
	v_lshrrev_b32_e32 v67, 16, v67
	v_add3_u32 v71, v49, v71, s72
	v_lshl_add_u64 v[72:73], v[58:59], 4, s[14:15]
	v_and_or_b32 v71, v71, s88, v67
	v_bfe_u32 v67, v50, 16, 1
	global_store_dwordx4 v[72:73], v[68:71], off
	v_add3_u32 v67, v50, v67, s72
	v_lshrrev_b32_e32 v67, 16, v67
	v_bfe_u32 v68, v51, 16, 1
	v_add3_u32 v68, v51, v68, s72
	v_and_or_b32 v68, v68, s88, v67
	v_bfe_u32 v67, v52, 16, 1
	v_add3_u32 v67, v52, v67, s72
	v_bfe_u32 v69, v53, 16, 1
	v_lshrrev_b32_e32 v67, 16, v67
	v_add3_u32 v69, v53, v69, s72
	v_and_or_b32 v69, v69, s88, v67
	v_bfe_u32 v67, v54, 16, 1
	v_add3_u32 v67, v54, v67, s72
	v_bfe_u32 v70, v55, 16, 1
	v_lshrrev_b32_e32 v67, 16, v67
	v_add3_u32 v70, v55, v70, s72
	v_and_or_b32 v70, v70, s88, v67
	v_bfe_u32 v67, v56, 16, 1
	v_add3_u32 v67, v56, v67, s72
	v_bfe_u32 v71, v57, 16, 1
	v_lshrrev_b32_e32 v67, 16, v67
	v_add3_u32 v71, v57, v71, s72
	v_and_or_b32 v71, v71, s88, v67
	s_mov_b64 s[14:15], 0
	global_store_dwordx4 v[72:73], v[68:71], off offset:1024

; #define GAS __attribute__((address_space(1)))
; #define WSB(F, off) ((bf16*)(wsq((F).ws) + (off)))
; __device__ __forceinline__ void ln_rows(const Frame& F, int idx, bool final_out, int row_lo, int row_hi, int gw0, int NGW, bool comb = false) {
;     ...
;         for (int r = 0; r < 2; ++r) { const int m = m0 + r * NGW; if (r == 1 && !two) break;
;         f32x4 v[4]; float s = 0.f;
; #pragma unroll
;         for (int j = 0; j < 2; ++j) { const v4u x = w[r][j]; v[2 * j] = (f32x4){bflo(x.x), bfhi(x.x), bflo(x.y), bfhi(x.y)}; v[2 * j + 1] = (f32x4){bflo(x.z), bfhi(x.z), bflo(x.w), bfhi(x.w)}; }
;         if (comb) {
;             const GAS f32x4* pa = (const GAS f32x4*)((const float*)WSB(F, WS_ACT) + (size_t)(m - MP) * D) + 2 * tc.lane; const GAS f32x4* pb = pa + (size_t)512 * D / 4;
; #pragma unroll
;             for (int j = 0; j < 2; ++j) { v[2 * j] = v[2 * j] * ALPHA + (pa[128 * j] + pb[128 * j]) * 0.5f; v[2 * j + 1] = v[2 * j + 1] * ALPHA + (pa[128 * j + 1] + pb[128 * j + 1]) * 0.5f; } }
; #pragma unroll
;         for (int j = 0; j < 4; ++j) s += (v[j].x + v[j].y) + (v[j].z + v[j].w);
;         const float mean = wave_sum(s) * (1.f / D); float s2 = 0.f;
; #pragma unroll
;         for (int j = 0; j < 4; ++j) { v[j] = v[j] - mean; s2 += (v[j].x * v[j].x + v[j].y * v[j].y) + (v[j].z * v[j].z + v[j].w * v[j].w); }
.LBB0_2176:
	s_andn2_b64 vcc, exec, s[6:7]
	s_cbranch_vccnz .LBB0_2168
	s_add_i32 s12, s10, 0xffff0000
	s_mov_b64 s[6:7], s[46:47]
	s_ashr_i32 s13, s12, 31
	s_lshl_b64 s[14:15], s[12:13], 12
	s_add_u32 s6, s6, s14
	s_addc_u32 s7, s7, s15
	v_lshl_add_u64 v[76:77], v[60:61], 4, s[6:7]
	s_mov_b64 s[6:7], 0x10300000
	v_lshl_add_u64 v[78:79], v[76:77], 0, s[6:7]
	s_mov_b64 s[6:7], 0x10500000
	v_lshl_add_u64 v[50:51], v[76:77], 0, s[6:7]
	s_mov_b32 s6, 0x10300000
	v_lshlrev_b32_e32 v72, 16, v34
	v_and_b32_e32 v73, 0xffff0000, v34
	v_add_co_u32_e32 v34, vcc, s6, v76
	v_lshlrev_b32_e32 v74, 16, v35
	v_and_b32_e32 v75, 0xffff0000, v35
	v_addc_co_u32_e32 v35, vcc, 0, v77, vcc
	s_mov_b32 s6, 0x10500000
	v_add_co_u32_e32 v80, vcc, s6, v76
	v_lshlrev_b32_e32 v54, 16, v38
	s_nop 0
	v_addc_co_u32_e32 v81, vcc, 0, v77, vcc
	v_and_b32_e32 v55, 0xffff0000, v38
	v_lshlrev_b32_e32 v56, 16, v39
	v_and_b32_e32 v57, 0xffff0000, v39
	v_lshlrev_b32_e32 v68, 16, v40
	v_and_b32_e32 v69, 0xffff0000, v40
	v_lshlrev_b32_e32 v70, 16, v41
	v_and_b32_e32 v71, 0xffff0000, v41
	v_lshlrev_b32_e32 v48, 16, v36
	v_and_b32_e32 v49, 0xffff0000, v36
	v_lshlrev_b32_e32 v46, 16, v37
	v_and_b32_e32 v47, 0xffff0000, v37
	global_load_dwordx4 v[34:37], v[34:35], off
	s_nop 0
	global_load_dwordx4 v[38:41], v[78:79], off offset:16
	global_load_dwordx4 v[42:45], v[80:81], off
	s_nop 0
	global_load_dwordx4 v[50:53], v[50:51], off offset:16
	s_mov_b64 s[6:7], 0x10500800
	s_waitcnt vmcnt(1)
	v_pk_add_f32 v[36:37], v[36:37], v[44:45]
	v_pk_add_f32 v[34:35], v[34:35], v[42:43]
	v_pk_mul_f32 v[36:37], v[36:37], 0.5 op_sel_hi:[1,0]
	v_pk_mul_f32 v[42:43], v[34:35], 0.5 op_sel_hi:[1,0]
	s_waitcnt vmcnt(0)
	v_pk_add_f32 v[40:41], v[40:41], v[52:53]
	v_pk_add_f32 v[38:39], v[38:39], v[50:51]
	v_pk_fma_f32 v[34:35], v[56:57], s[96:97], v[36:37] op_sel_hi:[1,0,1]
	v_pk_fma_f32 v[36:37], v[54:55], s[96:97], v[42:43] op_sel_hi:[1,0,1]
	v_pk_mul_f32 v[40:41], v[40:41], 0.5 op_sel_hi:[1,0]
	v_pk_mul_f32 v[42:43], v[38:39], 0.5 op_sel_hi:[1,0]
	v_pk_fma_f32 v[38:39], v[70:71], s[96:97], v[40:41] op_sel_hi:[1,0,1]
	v_pk_fma_f32 v[40:41], v[68:69], s[96:97], v[42:43] op_sel_hi:[1,0,1]
	v_lshl_add_u64 v[68:69], v[76:77], 0, s[6:7]
	global_load_dwordx4 v[50:53], v[78:79], off offset:2064
	global_load_dwordx4 v[42:45], v[78:79], off offset:2048
	global_load_dwordx4 v[54:57], v[80:81], off offset:2048
	s_nop 0
	global_load_dwordx4 v[68:71], v[68:69], off offset:16
	s_waitcnt vmcnt(1)
	v_pk_add_f32 v[44:45], v[44:45], v[56:57]
	s_waitcnt vmcnt(0)
	v_pk_add_f32 v[52:53], v[52:53], v[70:71]
	v_pk_add_f32 v[50:51], v[50:51], v[68:69]
	v_pk_add_f32 v[42:43], v[42:43], v[54:55]
	v_pk_mul_f32 v[52:53], v[52:53], 0.5 op_sel_hi:[1,0]
	v_pk_mul_f32 v[50:51], v[50:51], 0.5 op_sel_hi:[1,0]
	v_pk_mul_f32 v[44:45], v[44:45], 0.5 op_sel_hi:[1,0]
	v_pk_mul_f32 v[54:55], v[42:43], 0.5 op_sel_hi:[1,0]
	v_pk_fma_f32 v[46:47], v[46:47], s[96:97], v[52:53] op_sel_hi:[1,0,1]
	v_pk_fma_f32 v[48:49], v[48:49], s[96:97], v[50:51] op_sel_hi:[1,0,1]
	v_pk_mov_b32 v[50:51], v[36:37], v[34:35] op_sel:[1,0]
	v_mov_b32_e32 v52, v36
	v_mov_b32_e32 v53, v35
	v_pk_fma_f32 v[42:43], v[74:75], s[96:97], v[44:45] op_sel_hi:[1,0,1]
	v_pk_fma_f32 v[44:45], v[72:73], s[96:97], v[54:55] op_sel_hi:[1,0,1]
	v_pk_add_f32 v[50:51], v[50:51], v[52:53]
	v_pk_mov_b32 v[52:53], v[40:41], v[38:39] op_sel:[1,0]
	v_mov_b32_e32 v54, v40
	v_mov_b32_e32 v55, v39
	v_pk_add_f32 v[52:53], v[52:53], v[54:55]
	v_add_f32_e32 v50, v50, v51
	v_pk_add_f32 v[52:53], v[52:53], v[52:53] op_sel:[0,1] op_sel_hi:[1,0]
	v_add_f32_e32 v50, 0, v50
	v_add_f32_e32 v54, v44, v45
	v_add_f32_e32 v56, v42, v43
	v_mov_b32_e32 v51, v48
	v_mov_b32_e32 v53, v49
	v_mov_b32_e32 v55, v46
	v_mov_b32_e32 v57, v47
	v_pk_add_f32 v[50:51], v[50:51], v[52:53]
	v_pk_add_f32 v[52:53], v[54:55], v[56:57]
	s_nop 0
	v_pk_add_f32 v[50:51], v[50:51], v[52:53]
	s_nop 0
	v_add_f32_e32 v50, v50, v51
	s_nop 1
	v_add_f32_dpp v50, v50, v50 quad_perm:[1,0,3,2] row_mask:0xf bank_mask:0xf
	s_nop 1
	v_add_f32_dpp v50, v50, v50 quad_perm:[2,3,0,1] row_mask:0xf bank_mask:0xf
	s_nop 1
	v_add_f32_dpp v50, v50, v50 row_half_mirror row_mask:0xf bank_mask:0xf
	s_nop 1
	v_add_f32_dpp v50, v50, v50 row_mirror row_mask:0xf bank_mask:0xf
	v_mov_b32_e32 v51, v50
	v_mov_b32_e32 v66, v50
	s_nop 1
	v_permlane16_swap_b32_e32 v51, v66
	s_nop 1
	v_add_f32_e32 v50, v51, v66
	v_mov_b32_e32 v51, v50
	v_mov_b32_e32 v66, v50
	s_nop 1
	v_permlane32_swap_b32_e32 v51, v66
	s_nop 1
	v_add_f32_e32 v67, v51, v66
	v_fmamk_f32 v37, v67, 0xba800000, v37
	v_fmac_f32_e32 v36, 0xba800000, v67
	v_fmamk_f32 v35, v67, 0xba800000, v35
	v_fmac_f32_e32 v34, 0xba800000, v67
	v_pk_mul_f32 v[50:51], v[34:35], v[34:35]
	v_pk_mul_f32 v[52:53], v[36:37], v[36:37]
	v_fmamk_f32 v41, v67, 0xba800000, v41
	v_pk_mov_b32 v[54:55], v[52:53], v[50:51] op_sel:[1,0]
	v_mov_b32_e32 v53, v51
	v_pk_add_f32 v[50:51], v[54:55], v[52:53]
	v_fmac_f32_e32 v40, 0xba800000, v67
	v_fmamk_f32 v39, v67, 0xba800000, v39
	v_fmac_f32_e32 v38, 0xba800000, v67
	v_pk_add_f32 v[50:51], v[50:51], v[50:51] op_sel_hi:[0,1]
	v_pk_mul_f32 v[52:53], v[38:39], v[38:39]
	v_pk_mul_f32 v[54:55], v[40:41], v[40:41]
	v_fmac_f32_e32 v44, 0xba800000, v67
	v_pk_mov_b32 v[56:57], v[54:55], v[52:53] op_sel:[1,0]
	v_mov_b32_e32 v55, v53
; #define GAS __attribute__((address_space(1)))
; __device__ __forceinline__ unsigned pk2(float lo, float hi) { return f2bf(lo) | (f2bf(hi) << 16); }
; #define WSB(F, off) ((bf16*)(wsq((F).ws) + (off)))
; __device__ __forceinline__ void ln_rows(const Frame& F, int idx, bool final_out, int row_lo, int row_hi, int gw0, int NGW, bool comb = false) {
;     ...
;         for (int j = 0; j < 4; ++j) { v[j] = v[j] - mean; s2 += (v[j].x * v[j].x + v[j].y * v[j].y) + (v[j].z * v[j].z + v[j].w * v[j].w); }
;         const float rstd = 1.f / sqrtf(wave_sum(s2) * (1.f / D) + LN_EPS);
; #pragma unroll
;         for (int j = 0; j < 4; ++j) v[j] = v[j] * rstd * gv[j] + bv[j];
;         if (!final_out) { GAS v4u* o = (GAS v4u*)(WSB(F, WS_HB) + (size_t)m * D) + tc.lane;
; #pragma unroll
;             for (int j = 0; j < 2; ++j) o[64 * j] = (v4u){pk2(v[2 * j].x, v[2 * j].y), pk2(v[2 * j].z, v[2 * j].w), pk2(v[2 * j + 1].x, v[2 * j + 1].y), pk2(v[2 * j + 1].z, v[2 * j + 1].w)}; }
	v_fmamk_f32 v45, v67, 0xba800000, v45
	v_fmac_f32_e32 v42, 0xba800000, v67
	v_mul_f32_e32 v50, v44, v44
	v_pk_add_f32 v[52:53], v[56:57], v[54:55]
	v_fmamk_f32 v43, v67, 0xba800000, v43
	v_pk_fma_f32 v[54:55], v[44:45], v[44:45], v[50:51] op_sel_hi:[1,1,0]
	v_mul_f32_e32 v50, v42, v42
	v_pk_add_f32 v[52:53], v[52:53], v[52:53] op_sel_hi:[0,1]
	v_pk_fma_f32 v[56:57], v[42:43], v[42:43], v[50:51] op_sel_hi:[1,1,0]
	v_fmamk_f32 v47, v67, 0xba800000, v47
	v_fmac_f32_e32 v46, 0xba800000, v67
	v_fmamk_f32 v49, v67, 0xba800000, v49
	v_fmac_f32_e32 v48, 0xba800000, v67
	v_mul_f32_e32 v54, v48, v48
	v_mul_f32_e32 v56, v49, v49
	v_mul_f32_e32 v50, v46, v46
	v_mul_f32_e32 v52, v47, v47
	v_pk_add_f32 v[54:55], v[54:55], v[56:57]
	v_pk_add_f32 v[50:51], v[50:51], v[52:53]
	s_nop 0
	v_pk_add_f32 v[50:51], v[54:55], v[50:51]
	s_nop 0
	v_add_f32_e32 v50, v50, v51
	s_nop 1
	v_add_f32_dpp v50, v50, v50 quad_perm:[1,0,3,2] row_mask:0xf bank_mask:0xf
	s_nop 1
	v_add_f32_dpp v50, v50, v50 quad_perm:[2,3,0,1] row_mask:0xf bank_mask:0xf
	s_nop 1
	v_add_f32_dpp v50, v50, v50 row_half_mirror row_mask:0xf bank_mask:0xf
	s_nop 1
	v_add_f32_dpp v50, v50, v50 row_mirror row_mask:0xf bank_mask:0xf
	v_mov_b32_e32 v66, v50
	v_mov_b32_e32 v65, v50
	s_nop 1
	v_permlane16_swap_b32_e32 v66, v65
	s_nop 1
	v_add_f32_e32 v50, v66, v65
	v_mov_b32_e32 v66, v50
	v_mov_b32_e32 v65, v50
	s_nop 1
	v_permlane32_swap_b32_e32 v66, v65
	s_nop 1
	v_add_f32_e32 v1, v66, v65
	v_fmamk_f32 v1, v1, 0x3a800000, v235
	v_cmp_gt_f32_e32 vcc, s89, v1
	v_mul_f32_e32 v50, 0x4f800000, v1
	s_nop 0
	v_cndmask_b32_e32 v1, v1, v50, vcc
	v_sqrt_f32_e32 v50, v1
	s_nop 0
	v_add_u32_e32 v51, -1, v50
	v_fma_f32 v52, -v51, v50, v1
	v_cmp_ge_f32_e64 s[6:7], 0, v52
	v_add_u32_e32 v52, 1, v50
	s_nop 0
	v_cndmask_b32_e64 v51, v50, v51, s[6:7]
	v_fma_f32 v50, -v52, v50, v1
	v_cmp_lt_f32_e64 s[6:7], 0, v50
	s_nop 1
	v_cndmask_b32_e64 v50, v51, v52, s[6:7]
	v_mul_f32_e32 v51, 0x37800000, v50
	v_cndmask_b32_e32 v50, v50, v51, vcc
	v_cmp_class_f32_e32 vcc, v1, v236
	s_nop 1
	v_cndmask_b32_e32 v1, v50, v1, vcc
	v_div_scale_f32 v50, s[6:7], v1, v1, 1.0
	v_rcp_f32_e32 v51, v50
	s_mov_b64 s[6:7], -1
	v_fma_f32 v52, -v50, v51, 1.0
	v_fmac_f32_e32 v51, v52, v51
	v_div_scale_f32 v52, vcc, 1.0, v1, 1.0
	v_mul_f32_e32 v53, v52, v51
	v_fma_f32 v54, -v50, v53, v52
	v_fmac_f32_e32 v53, v54, v51
	v_fma_f32 v50, -v50, v53, v52
	v_div_fmas_f32 v50, v50, v51, v53
	v_div_fixup_f32 v50, v50, v1, 1.0
	v_pk_mul_f32 v[52:53], v[36:37], v[50:51] op_sel_hi:[1,0]
	v_pk_mul_f32 v[34:35], v[34:35], v[50:51] op_sel_hi:[1,0]
	v_pk_mul_f32 v[38:39], v[38:39], v[50:51] op_sel_hi:[1,0]
	v_pk_fma_f32 v[36:37], v[8:9], v[34:35], v[16:17]
	v_pk_fma_f32 v[34:35], v[6:7], v[52:53], v[14:15]
	v_pk_mul_f32 v[52:53], v[40:41], v[50:51] op_sel_hi:[1,0]
	v_pk_fma_f32 v[40:41], v[4:5], v[38:39], v[12:13]
	v_pk_fma_f32 v[38:39], v[2:3], v[52:53], v[10:11]
	v_pk_mul_f32 v[52:53], v[44:45], v[50:51] op_sel_hi:[1,0]
	v_pk_mul_f32 v[42:43], v[42:43], v[50:51] op_sel_hi:[1,0]
	v_pk_mul_f32 v[46:47], v[46:47], v[50:51] op_sel_hi:[1,0]
	v_pk_fma_f32 v[44:45], v[24:25], v[42:43], v[32:33]
	v_pk_fma_f32 v[42:43], v[22:23], v[52:53], v[30:31]
	v_pk_mul_f32 v[52:53], v[48:49], v[50:51] op_sel_hi:[1,0]
	v_pk_fma_f32 v[48:49], v[20:21], v[46:47], v[28:29]
	v_pk_fma_f32 v[46:47], v[18:19], v[52:53], v[26:27]
	s_and_b64 vcc, exec, s[4:5]
	s_cbranch_vccnz .LBB0_2179
	v_bfe_u32 v1, v34, 16, 1
	v_add3_u32 v1, v34, v1, s72
	v_bfe_u32 v50, v35, 16, 1
	v_lshrrev_b32_e32 v1, 16, v1
	v_add3_u32 v50, v35, v50, s72
	v_and_or_b32 v50, v50, s88, v1
	v_bfe_u32 v1, v36, 16, 1
	v_add3_u32 v1, v36, v1, s72
	v_bfe_u32 v51, v37, 16, 1
	s_mov_b64 s[4:5], s[46:47]
	s_ashr_i32 s11, s10, 31
	v_lshrrev_b32_e32 v1, 16, v1
	v_add3_u32 v51, v37, v51, s72
	s_lshl_b64 s[6:7], s[10:11], 11
	v_and_or_b32 v51, v51, s88, v1
	v_bfe_u32 v1, v38, 16, 1
	s_add_u32 s4, s4, s6
	v_add3_u32 v1, v38, v1, s72
	v_bfe_u32 v52, v39, 16, 1
	s_addc_u32 s5, s5, s7
	v_lshrrev_b32_e32 v1, 16, v1
	v_add3_u32 v52, v39, v52, s72
	v_lshl_add_u64 v[54:55], v[58:59], 4, s[4:5]
	s_mov_b64 s[4:5], 0x8200000
	v_and_or_b32 v52, v52, s88, v1
	v_bfe_u32 v1, v40, 16, 1
	v_lshl_add_u64 v[56:57], v[54:55], 0, s[4:5]
	v_add3_u32 v1, v40, v1, s72
	v_bfe_u32 v53, v41, 16, 1
	s_mov_b32 s4, 0x8200000
	v_lshrrev_b32_e32 v1, 16, v1
	v_add3_u32 v53, v41, v53, s72
	v_add_co_u32_e32 v54, vcc, s4, v54
	v_and_or_b32 v53, v53, s88, v1
	s_nop 0
	v_addc_co_u32_e32 v55, vcc, 0, v55, vcc
	v_bfe_u32 v1, v42, 16, 1
	global_store_dwordx4 v[54:55], v[50:53], off
	v_add3_u32 v1, v42, v1, s72
	v_lshrrev_b32_e32 v1, 16, v1
	v_bfe_u32 v50, v43, 16, 1
	v_add3_u32 v50, v43, v50, s72
	v_and_or_b32 v50, v50, s88, v1
	v_bfe_u32 v1, v44, 16, 1
	v_add3_u32 v1, v44, v1, s72
	v_bfe_u32 v51, v45, 16, 1
	v_lshrrev_b32_e32 v1, 16, v1
	v_add3_u32 v51, v45, v51, s72
	v_and_or_b32 v51, v51, s88, v1
	v_bfe_u32 v1, v46, 16, 1
	v_add3_u32 v1, v46, v1, s72
	v_bfe_u32 v52, v47, 16, 1
	v_lshrrev_b32_e32 v1, 16, v1
	v_add3_u32 v52, v47, v52, s72
	v_and_or_b32 v52, v52, s88, v1
	v_bfe_u32 v1, v48, 16, 1
	v_add3_u32 v1, v48, v1, s72
	v_bfe_u32 v53, v49, 16, 1
	v_lshrrev_b32_e32 v1, 16, v1
	v_add3_u32 v53, v49, v53, s72
	v_and_or_b32 v53, v53, s88, v1
	s_mov_b64 s[6:7], 0
	global_store_dwordx4 v[56:57], v[50:53], off offset:1024
